# accumulator zeroing at unit start with v_mov_b64 (half the instructions) and nt hint on the streaming epilogue stores (hid, hb, out)
# baseline (speedup 1.0000x reference)
.LBB0_803:
	s_lshl_b32 s2, s0, 8
	v_readlane_b32 s0, v251, 20
	v_readlane_b32 s1, v251, 21
	v_readlane_b32 s26, v251, 24
	v_readlane_b32 s27, v251, 25
	v_and_b32_e32 v148, 0x60, v145
	v_and_b32_e32 v149, 16, v209
	v_and_b32_e32 v150, 32, v209
	v_lshrrev_b32_e32 v150, 2, v150
	v_or3_b32 v148, v148, v149, v150
	v_lshl_or_b32 v148, s10, 8, v148
	v_add_u32_e32 v149, s2, v143
	v_lshlrev_b32_e32 v150, 11, v149
	v_lshl_add_u32 v136, v148, 1, v150
	v_xor_b32_e32 v137, 16, v209
	v_xor_b32_e32 v138, 32, v209
	v_lshlrev_b32_e32 v137, 2, v137
	v_lshlrev_b32_e32 v138, 2, v138
	s_add_u32 s28, s0, 0x0
	s_addc_u32 s29, s1, 0
	s_add_u32 s100, s26, 0x0
	s_addc_u32 s101, s27, 0
	global_load_dwordx4 v[160:163], v136, s[28:29]
	global_load_dwordx4 v[164:167], v136, s[100:101]
	s_add_u32 s28, s0, 0x0
	s_addc_u32 s29, s1, 0
	s_add_u32 s100, s26, 0x0
	s_addc_u32 s101, s27, 0
	global_load_dwordx4 v[174:177], v136, s[28:29] offset:256
	global_load_dwordx4 v[178:181], v136, s[100:101] offset:256
	s_add_u32 s28, s0, 0x8000
	s_addc_u32 s29, s1, 0
	s_add_u32 s100, s26, 0x8000
	s_addc_u32 s101, s27, 0
	global_load_dwordx4 v[182:185], v136, s[28:29]
	global_load_dwordx4 v[186:189], v136, s[100:101]
	s_add_u32 s28, s0, 0x8000
	s_addc_u32 s29, s1, 0
	s_add_u32 s100, s26, 0x8000
	s_addc_u32 s101, s27, 0
	global_load_dwordx4 v[190:193], v136, s[28:29] offset:256
	global_load_dwordx4 v[194:197], v136, s[100:101] offset:256
	s_add_u32 s28, s0, 0x10000
	s_addc_u32 s29, s1, 0
	s_add_u32 s100, s26, 0x10000
	s_addc_u32 s101, s27, 0
	global_load_dwordx4 v[198:201], v136, s[28:29]
	global_load_dwordx4 v[202:205], v136, s[100:101]
	s_add_u32 s28, s0, 0x10000
	s_addc_u32 s29, s1, 0
	s_add_u32 s100, s26, 0x10000
	s_addc_u32 s101, s27, 0
	global_load_dwordx4 v[222:225], v136, s[28:29] offset:256
	global_load_dwordx4 v[226:229], v136, s[100:101] offset:256
	s_waitcnt vmcnt(10)
	v_permlane16_swap_b32_e32 v126, v122
	v_permlane16_swap_b32_e32 v127, v123
	v_permlane16_swap_b32_e32 v128, v124
	v_permlane16_swap_b32_e32 v129, v125
	v_mul_f32_e32 v126, 0xbfb8aa3b, v126
	v_mul_f32_e32 v127, 0xbfb8aa3b, v127
	v_mul_f32_e32 v128, 0xbfb8aa3b, v128
	v_mul_f32_e32 v129, 0xbfb8aa3b, v129
	v_mul_f32_e32 v122, 0xbfb8aa3b, v122
	v_mul_f32_e32 v123, 0xbfb8aa3b, v123
	v_mul_f32_e32 v124, 0xbfb8aa3b, v124
	v_mul_f32_e32 v125, 0xbfb8aa3b, v125
	v_exp_f32_e32 v126, v126
	v_exp_f32_e32 v127, v127
	v_exp_f32_e32 v128, v128
	v_exp_f32_e32 v129, v129
	v_exp_f32_e32 v122, v122
	v_exp_f32_e32 v123, v123
	v_exp_f32_e32 v124, v124
	v_exp_f32_e32 v125, v125
	v_add_f32_e32 v126, 1.0, v126
	v_add_f32_e32 v127, 1.0, v127
	v_add_f32_e32 v128, 1.0, v128
	v_add_f32_e32 v129, 1.0, v129
	v_add_f32_e32 v122, 1.0, v122
	v_add_f32_e32 v123, 1.0, v123
	v_add_f32_e32 v124, 1.0, v124
	v_add_f32_e32 v125, 1.0, v125
	v_rcp_f32_e32 v126, v126
	v_rcp_f32_e32 v127, v127
	v_rcp_f32_e32 v128, v128
	v_rcp_f32_e32 v129, v129
	v_rcp_f32_e32 v122, v122
	v_rcp_f32_e32 v123, v123
	v_rcp_f32_e32 v124, v124
	v_rcp_f32_e32 v125, v125
	v_lshlrev_b32_e32 v148, 16, v160
	v_lshlrev_b32_e32 v149, 16, v164
	v_and_b32_e32 v150, 0xffff0000, v160
	v_and_b32_e32 v151, 0xffff0000, v164
	v_fma_f32 v126, v126, v149, v148
	v_fma_f32 v127, v127, v151, v150
	v_lshlrev_b32_e32 v152, 16, v161
	v_lshlrev_b32_e32 v153, 16, v165
	v_and_b32_e32 v154, 0xffff0000, v161
	v_and_b32_e32 v155, 0xffff0000, v165
	v_fma_f32 v128, v128, v153, v152
	v_fma_f32 v129, v129, v155, v154
	v_lshlrev_b32_e32 v148, 16, v162
	v_lshlrev_b32_e32 v149, 16, v166
	v_and_b32_e32 v150, 0xffff0000, v162
	v_and_b32_e32 v151, 0xffff0000, v166
	v_fma_f32 v122, v122, v149, v148
	v_fma_f32 v123, v123, v151, v150
	v_lshlrev_b32_e32 v152, 16, v163
	v_lshlrev_b32_e32 v153, 16, v167
	v_and_b32_e32 v154, 0xffff0000, v163
	v_and_b32_e32 v155, 0xffff0000, v167
	v_fma_f32 v124, v124, v153, v152
	v_fma_f32 v125, v125, v155, v154
	v_cvt_pk_bf16_f32 v160, v126, v127
	v_cvt_pk_bf16_f32 v161, v128, v129
	v_cvt_pk_bf16_f32 v162, v122, v123
	v_cvt_pk_bf16_f32 v163, v124, v125
	s_add_u32 s28, s0, 0x0
	s_addc_u32 s29, s1, 0
	global_store_dwordx4 v136, v[160:163], s[28:29] nt
	s_add_u32 s28, s0, 0x18000
	s_addc_u32 s29, s1, 0
	s_add_u32 s100, s26, 0x18000
	s_addc_u32 s101, s27, 0
	global_load_dwordx4 v[126:129], v136, s[28:29]
	global_load_dwordx4 v[122:125], v136, s[100:101]
	v_lshlrev_b32_e32 v148, 16, v160
	v_lshlrev_b32_e32 v149, 16, v161
	v_and_b32_e32 v150, 0xffff0000, v160
	v_and_b32_e32 v151, 0xffff0000, v161
	v_lshlrev_b32_e32 v152, 16, v162
	v_lshlrev_b32_e32 v153, 16, v163
	v_and_b32_e32 v154, 0xffff0000, v162
	v_and_b32_e32 v155, 0xffff0000, v163
	v_pk_mul_f32 v[150:151], v[150:151], v[150:151]
	v_pk_mul_f32 v[154:155], v[154:155], v[154:155]
	v_pk_fma_f32 v[148:149], v[148:149], v[148:149], v[150:151]
	v_pk_fma_f32 v[152:153], v[152:153], v[152:153], v[154:155]
	s_nop 0
	v_add_f32_e32 v148, v148, v149
	v_add_f32_e32 v152, v152, v153
	v_add_f32_e32 v156, v148, v152
	s_waitcnt vmcnt(11)
	v_permlane16_swap_b32_e32 v118, v114
	v_permlane16_swap_b32_e32 v119, v115
	v_permlane16_swap_b32_e32 v120, v116
	v_permlane16_swap_b32_e32 v121, v117
	v_mul_f32_e32 v118, 0xbfb8aa3b, v118
	v_mul_f32_e32 v119, 0xbfb8aa3b, v119
	v_mul_f32_e32 v120, 0xbfb8aa3b, v120
	v_mul_f32_e32 v121, 0xbfb8aa3b, v121
	v_mul_f32_e32 v114, 0xbfb8aa3b, v114
	v_mul_f32_e32 v115, 0xbfb8aa3b, v115
	v_mul_f32_e32 v116, 0xbfb8aa3b, v116
	v_mul_f32_e32 v117, 0xbfb8aa3b, v117
	v_exp_f32_e32 v118, v118
	v_exp_f32_e32 v119, v119
	v_exp_f32_e32 v120, v120
	v_exp_f32_e32 v121, v121
	v_exp_f32_e32 v114, v114
	v_exp_f32_e32 v115, v115
	v_exp_f32_e32 v116, v116
	v_exp_f32_e32 v117, v117
	v_add_f32_e32 v118, 1.0, v118
	v_add_f32_e32 v119, 1.0, v119
	v_add_f32_e32 v120, 1.0, v120
	v_add_f32_e32 v121, 1.0, v121
	v_add_f32_e32 v114, 1.0, v114
	v_add_f32_e32 v115, 1.0, v115
	v_add_f32_e32 v116, 1.0, v116
	v_add_f32_e32 v117, 1.0, v117
	v_rcp_f32_e32 v118, v118
	v_rcp_f32_e32 v119, v119
	v_rcp_f32_e32 v120, v120
	v_rcp_f32_e32 v121, v121
	v_rcp_f32_e32 v114, v114
	v_rcp_f32_e32 v115, v115
	v_rcp_f32_e32 v116, v116
	v_rcp_f32_e32 v117, v117
	v_lshlrev_b32_e32 v148, 16, v174
	v_lshlrev_b32_e32 v149, 16, v178
	v_and_b32_e32 v150, 0xffff0000, v174
	v_and_b32_e32 v151, 0xffff0000, v178
	v_fma_f32 v118, v118, v149, v148
	v_fma_f32 v119, v119, v151, v150
	v_lshlrev_b32_e32 v152, 16, v175
	v_lshlrev_b32_e32 v153, 16, v179
	v_and_b32_e32 v154, 0xffff0000, v175
	v_and_b32_e32 v155, 0xffff0000, v179
	v_fma_f32 v120, v120, v153, v152
	v_fma_f32 v121, v121, v155, v154
	v_lshlrev_b32_e32 v148, 16, v176
	v_lshlrev_b32_e32 v149, 16, v180
	v_and_b32_e32 v150, 0xffff0000, v176
	v_and_b32_e32 v151, 0xffff0000, v180
	v_fma_f32 v114, v114, v149, v148
	v_fma_f32 v115, v115, v151, v150
	v_lshlrev_b32_e32 v152, 16, v177
	v_lshlrev_b32_e32 v153, 16, v181
	v_and_b32_e32 v154, 0xffff0000, v177
	v_and_b32_e32 v155, 0xffff0000, v181
	v_fma_f32 v116, v116, v153, v152
	v_fma_f32 v117, v117, v155, v154
	v_cvt_pk_bf16_f32 v174, v118, v119
	v_cvt_pk_bf16_f32 v175, v120, v121
	v_cvt_pk_bf16_f32 v176, v114, v115
	v_cvt_pk_bf16_f32 v177, v116, v117
	s_add_u32 s28, s0, 0x0
	s_addc_u32 s29, s1, 0
	global_store_dwordx4 v136, v[174:177], s[28:29] offset:256 nt
	s_add_u32 s28, s0, 0x18000
	s_addc_u32 s29, s1, 0
	s_add_u32 s100, s26, 0x18000
	s_addc_u32 s101, s27, 0
	global_load_dwordx4 v[118:121], v136, s[28:29] offset:256
	global_load_dwordx4 v[114:117], v136, s[100:101] offset:256
	v_lshlrev_b32_e32 v148, 16, v174
	v_lshlrev_b32_e32 v149, 16, v175
	v_and_b32_e32 v150, 0xffff0000, v174
	v_and_b32_e32 v151, 0xffff0000, v175
	v_lshlrev_b32_e32 v152, 16, v176
	v_lshlrev_b32_e32 v153, 16, v177
	v_and_b32_e32 v154, 0xffff0000, v176
	v_and_b32_e32 v155, 0xffff0000, v177
	v_pk_mul_f32 v[150:151], v[150:151], v[150:151]
	v_pk_mul_f32 v[154:155], v[154:155], v[154:155]
	v_pk_fma_f32 v[148:149], v[148:149], v[148:149], v[150:151]
	v_pk_fma_f32 v[152:153], v[152:153], v[152:153], v[154:155]
	s_nop 0
	v_add_f32_e32 v148, v148, v149
	v_add_f32_e32 v152, v152, v153
	v_add_f32_e32 v156, v156, v148
	v_add_f32_e32 v156, v156, v152
	s_waitcnt vmcnt(12)
	v_permlane16_swap_b32_e32 v110, v106
	v_permlane16_swap_b32_e32 v111, v107
	v_permlane16_swap_b32_e32 v112, v108
	v_permlane16_swap_b32_e32 v113, v109
	v_mul_f32_e32 v110, 0xbfb8aa3b, v110
	v_mul_f32_e32 v111, 0xbfb8aa3b, v111
	v_mul_f32_e32 v112, 0xbfb8aa3b, v112
	v_mul_f32_e32 v113, 0xbfb8aa3b, v113
	v_mul_f32_e32 v106, 0xbfb8aa3b, v106
	v_mul_f32_e32 v107, 0xbfb8aa3b, v107
	v_mul_f32_e32 v108, 0xbfb8aa3b, v108
	v_mul_f32_e32 v109, 0xbfb8aa3b, v109
	v_exp_f32_e32 v110, v110
	v_exp_f32_e32 v111, v111
	v_exp_f32_e32 v112, v112
	v_exp_f32_e32 v113, v113
	v_exp_f32_e32 v106, v106
	v_exp_f32_e32 v107, v107
	v_exp_f32_e32 v108, v108
	v_exp_f32_e32 v109, v109
	v_add_f32_e32 v110, 1.0, v110
	v_add_f32_e32 v111, 1.0, v111
	v_add_f32_e32 v112, 1.0, v112
	v_add_f32_e32 v113, 1.0, v113
	v_add_f32_e32 v106, 1.0, v106
	v_add_f32_e32 v107, 1.0, v107
	v_add_f32_e32 v108, 1.0, v108
	v_add_f32_e32 v109, 1.0, v109
	v_rcp_f32_e32 v110, v110
	v_rcp_f32_e32 v111, v111
	v_rcp_f32_e32 v112, v112
	v_rcp_f32_e32 v113, v113
	v_rcp_f32_e32 v106, v106
	v_rcp_f32_e32 v107, v107
	v_rcp_f32_e32 v108, v108
	v_rcp_f32_e32 v109, v109
	v_lshlrev_b32_e32 v148, 16, v182
	v_lshlrev_b32_e32 v149, 16, v186
	v_and_b32_e32 v150, 0xffff0000, v182
	v_and_b32_e32 v151, 0xffff0000, v186
	v_fma_f32 v110, v110, v149, v148
	v_fma_f32 v111, v111, v151, v150
	v_lshlrev_b32_e32 v152, 16, v183
	v_lshlrev_b32_e32 v153, 16, v187
	v_and_b32_e32 v154, 0xffff0000, v183
	v_and_b32_e32 v155, 0xffff0000, v187
	v_fma_f32 v112, v112, v153, v152
	v_fma_f32 v113, v113, v155, v154
	v_lshlrev_b32_e32 v148, 16, v184
	v_lshlrev_b32_e32 v149, 16, v188
	v_and_b32_e32 v150, 0xffff0000, v184
	v_and_b32_e32 v151, 0xffff0000, v188
	v_fma_f32 v106, v106, v149, v148
	v_fma_f32 v107, v107, v151, v150
	v_lshlrev_b32_e32 v152, 16, v185
	v_lshlrev_b32_e32 v153, 16, v189
	v_and_b32_e32 v154, 0xffff0000, v185
	v_and_b32_e32 v155, 0xffff0000, v189
	v_fma_f32 v108, v108, v153, v152
	v_fma_f32 v109, v109, v155, v154
	v_cvt_pk_bf16_f32 v182, v110, v111
	v_cvt_pk_bf16_f32 v183, v112, v113
	v_cvt_pk_bf16_f32 v184, v106, v107
	v_cvt_pk_bf16_f32 v185, v108, v109
	s_add_u32 s28, s0, 0x8000
	s_addc_u32 s29, s1, 0
	global_store_dwordx4 v136, v[182:185], s[28:29] nt
	s_add_u32 s28, s0, 0x40000
	s_addc_u32 s29, s1, 0
	s_add_u32 s100, s26, 0x40000
	s_addc_u32 s101, s27, 0
	global_load_dwordx4 v[110:113], v136, s[28:29]
	global_load_dwordx4 v[106:109], v136, s[100:101]
	v_lshlrev_b32_e32 v148, 16, v182
	v_lshlrev_b32_e32 v149, 16, v183
	v_and_b32_e32 v150, 0xffff0000, v182
	v_and_b32_e32 v151, 0xffff0000, v183
	v_lshlrev_b32_e32 v152, 16, v184
	v_lshlrev_b32_e32 v153, 16, v185
	v_and_b32_e32 v154, 0xffff0000, v184
	v_and_b32_e32 v155, 0xffff0000, v185
	v_pk_mul_f32 v[150:151], v[150:151], v[150:151]
	v_pk_mul_f32 v[154:155], v[154:155], v[154:155]
	v_pk_fma_f32 v[148:149], v[148:149], v[148:149], v[150:151]
	v_pk_fma_f32 v[152:153], v[152:153], v[152:153], v[154:155]
	s_nop 0
	v_add_f32_e32 v148, v148, v149
	v_add_f32_e32 v152, v152, v153
	v_add_f32_e32 v157, v148, v152
	s_waitcnt vmcnt(13)
	v_permlane16_swap_b32_e32 v102, v98
	v_permlane16_swap_b32_e32 v103, v99
	v_permlane16_swap_b32_e32 v104, v100
	v_permlane16_swap_b32_e32 v105, v101
	v_mul_f32_e32 v102, 0xbfb8aa3b, v102
	v_mul_f32_e32 v103, 0xbfb8aa3b, v103
	v_mul_f32_e32 v104, 0xbfb8aa3b, v104
	v_mul_f32_e32 v105, 0xbfb8aa3b, v105
	v_mul_f32_e32 v98, 0xbfb8aa3b, v98
	v_mul_f32_e32 v99, 0xbfb8aa3b, v99
	v_mul_f32_e32 v100, 0xbfb8aa3b, v100
	v_mul_f32_e32 v101, 0xbfb8aa3b, v101
	v_exp_f32_e32 v102, v102
	v_exp_f32_e32 v103, v103
	v_exp_f32_e32 v104, v104
	v_exp_f32_e32 v105, v105
	v_exp_f32_e32 v98, v98
	v_exp_f32_e32 v99, v99
	v_exp_f32_e32 v100, v100
	v_exp_f32_e32 v101, v101
	v_add_f32_e32 v102, 1.0, v102
	v_add_f32_e32 v103, 1.0, v103
	v_add_f32_e32 v104, 1.0, v104
	v_add_f32_e32 v105, 1.0, v105
	v_add_f32_e32 v98, 1.0, v98
	v_add_f32_e32 v99, 1.0, v99
	v_add_f32_e32 v100, 1.0, v100
	v_add_f32_e32 v101, 1.0, v101
	v_rcp_f32_e32 v102, v102
	v_rcp_f32_e32 v103, v103
	v_rcp_f32_e32 v104, v104
	v_rcp_f32_e32 v105, v105
	v_rcp_f32_e32 v98, v98
	v_rcp_f32_e32 v99, v99
	v_rcp_f32_e32 v100, v100
	v_rcp_f32_e32 v101, v101
	v_lshlrev_b32_e32 v148, 16, v190
	v_lshlrev_b32_e32 v149, 16, v194
	v_and_b32_e32 v150, 0xffff0000, v190
	v_and_b32_e32 v151, 0xffff0000, v194
	v_fma_f32 v102, v102, v149, v148
	v_fma_f32 v103, v103, v151, v150
	v_lshlrev_b32_e32 v152, 16, v191
	v_lshlrev_b32_e32 v153, 16, v195
	v_and_b32_e32 v154, 0xffff0000, v191
	v_and_b32_e32 v155, 0xffff0000, v195
	v_fma_f32 v104, v104, v153, v152
	v_fma_f32 v105, v105, v155, v154
	v_lshlrev_b32_e32 v148, 16, v192
	v_lshlrev_b32_e32 v149, 16, v196
	v_and_b32_e32 v150, 0xffff0000, v192
	v_and_b32_e32 v151, 0xffff0000, v196
	v_fma_f32 v98, v98, v149, v148
	v_fma_f32 v99, v99, v151, v150
	v_lshlrev_b32_e32 v152, 16, v193
	v_lshlrev_b32_e32 v153, 16, v197
	v_and_b32_e32 v154, 0xffff0000, v193
	v_and_b32_e32 v155, 0xffff0000, v197
	v_fma_f32 v100, v100, v153, v152
	v_fma_f32 v101, v101, v155, v154
	v_cvt_pk_bf16_f32 v190, v102, v103
	v_cvt_pk_bf16_f32 v191, v104, v105
	v_cvt_pk_bf16_f32 v192, v98, v99
	v_cvt_pk_bf16_f32 v193, v100, v101
	s_add_u32 s28, s0, 0x8000
	s_addc_u32 s29, s1, 0
	global_store_dwordx4 v136, v[190:193], s[28:29] offset:256 nt
	s_add_u32 s28, s0, 0x40000
	s_addc_u32 s29, s1, 0
	s_add_u32 s100, s26, 0x40000
	s_addc_u32 s101, s27, 0
	global_load_dwordx4 v[102:105], v136, s[28:29] offset:256
	global_load_dwordx4 v[98:101], v136, s[100:101] offset:256
	v_lshlrev_b32_e32 v148, 16, v190
	v_lshlrev_b32_e32 v149, 16, v191
	v_and_b32_e32 v150, 0xffff0000, v190
	v_and_b32_e32 v151, 0xffff0000, v191
	v_lshlrev_b32_e32 v152, 16, v192
	v_lshlrev_b32_e32 v153, 16, v193
	v_and_b32_e32 v154, 0xffff0000, v192
	v_and_b32_e32 v155, 0xffff0000, v193
	v_pk_mul_f32 v[150:151], v[150:151], v[150:151]
	v_pk_mul_f32 v[154:155], v[154:155], v[154:155]
	v_pk_fma_f32 v[148:149], v[148:149], v[148:149], v[150:151]
	v_pk_fma_f32 v[152:153], v[152:153], v[152:153], v[154:155]
	s_nop 0
	v_add_f32_e32 v148, v148, v149
	v_add_f32_e32 v152, v152, v153
	v_add_f32_e32 v157, v157, v148
	v_add_f32_e32 v157, v157, v152
	s_waitcnt vmcnt(14)
	v_permlane16_swap_b32_e32 v92, v88
	v_permlane16_swap_b32_e32 v93, v89
	v_permlane16_swap_b32_e32 v94, v90
	v_permlane16_swap_b32_e32 v95, v91
	v_mul_f32_e32 v92, 0xbfb8aa3b, v92
	v_mul_f32_e32 v93, 0xbfb8aa3b, v93
	v_mul_f32_e32 v94, 0xbfb8aa3b, v94
	v_mul_f32_e32 v95, 0xbfb8aa3b, v95
	v_mul_f32_e32 v88, 0xbfb8aa3b, v88
	v_mul_f32_e32 v89, 0xbfb8aa3b, v89
	v_mul_f32_e32 v90, 0xbfb8aa3b, v90
	v_mul_f32_e32 v91, 0xbfb8aa3b, v91
	v_exp_f32_e32 v92, v92
	v_exp_f32_e32 v93, v93
	v_exp_f32_e32 v94, v94
	v_exp_f32_e32 v95, v95
	v_exp_f32_e32 v88, v88
	v_exp_f32_e32 v89, v89
	v_exp_f32_e32 v90, v90
	v_exp_f32_e32 v91, v91
	v_add_f32_e32 v92, 1.0, v92
	v_add_f32_e32 v93, 1.0, v93
	v_add_f32_e32 v94, 1.0, v94
	v_add_f32_e32 v95, 1.0, v95
	v_add_f32_e32 v88, 1.0, v88
	v_add_f32_e32 v89, 1.0, v89
	v_add_f32_e32 v90, 1.0, v90
	v_add_f32_e32 v91, 1.0, v91
	v_rcp_f32_e32 v92, v92
	v_rcp_f32_e32 v93, v93
	v_rcp_f32_e32 v94, v94
	v_rcp_f32_e32 v95, v95
	v_rcp_f32_e32 v88, v88
	v_rcp_f32_e32 v89, v89
	v_rcp_f32_e32 v90, v90
	v_rcp_f32_e32 v91, v91
	v_lshlrev_b32_e32 v148, 16, v198
	v_lshlrev_b32_e32 v149, 16, v202
	v_and_b32_e32 v150, 0xffff0000, v198
	v_and_b32_e32 v151, 0xffff0000, v202
	v_fma_f32 v92, v92, v149, v148
	v_fma_f32 v93, v93, v151, v150
	v_lshlrev_b32_e32 v152, 16, v199
	v_lshlrev_b32_e32 v153, 16, v203
	v_and_b32_e32 v154, 0xffff0000, v199
	v_and_b32_e32 v155, 0xffff0000, v203
	v_fma_f32 v94, v94, v153, v152
	v_fma_f32 v95, v95, v155, v154
	v_lshlrev_b32_e32 v148, 16, v200
	v_lshlrev_b32_e32 v149, 16, v204
	v_and_b32_e32 v150, 0xffff0000, v200
	v_and_b32_e32 v151, 0xffff0000, v204
	v_fma_f32 v88, v88, v149, v148
	v_fma_f32 v89, v89, v151, v150
	v_lshlrev_b32_e32 v152, 16, v201
	v_lshlrev_b32_e32 v153, 16, v205
	v_and_b32_e32 v154, 0xffff0000, v201
	v_and_b32_e32 v155, 0xffff0000, v205
	v_fma_f32 v90, v90, v153, v152
	v_fma_f32 v91, v91, v155, v154
	v_cvt_pk_bf16_f32 v198, v92, v93
	v_cvt_pk_bf16_f32 v199, v94, v95
	v_cvt_pk_bf16_f32 v200, v88, v89
	v_cvt_pk_bf16_f32 v201, v90, v91
	s_add_u32 s28, s0, 0x10000
	s_addc_u32 s29, s1, 0
	global_store_dwordx4 v136, v[198:201], s[28:29] nt
	s_add_u32 s28, s0, 0x48000
	s_addc_u32 s29, s1, 0
	s_add_u32 s100, s26, 0x48000
	s_addc_u32 s101, s27, 0
	global_load_dwordx4 v[92:95], v136, s[28:29]
	global_load_dwordx4 v[88:91], v136, s[100:101]
	v_lshlrev_b32_e32 v148, 16, v198
	v_lshlrev_b32_e32 v149, 16, v199
	v_and_b32_e32 v150, 0xffff0000, v198
	v_and_b32_e32 v151, 0xffff0000, v199
	v_lshlrev_b32_e32 v152, 16, v200
	v_lshlrev_b32_e32 v153, 16, v201
	v_and_b32_e32 v154, 0xffff0000, v200
	v_and_b32_e32 v155, 0xffff0000, v201
	v_pk_mul_f32 v[150:151], v[150:151], v[150:151]
	v_pk_mul_f32 v[154:155], v[154:155], v[154:155]
	v_pk_fma_f32 v[148:149], v[148:149], v[148:149], v[150:151]
	v_pk_fma_f32 v[152:153], v[152:153], v[152:153], v[154:155]
	s_nop 0
	v_add_f32_e32 v148, v148, v149
	v_add_f32_e32 v152, v152, v153
	v_add_f32_e32 v158, v148, v152
	s_waitcnt vmcnt(15)
	v_permlane16_swap_b32_e32 v84, v80
	v_permlane16_swap_b32_e32 v85, v81
	v_permlane16_swap_b32_e32 v86, v82
	v_permlane16_swap_b32_e32 v87, v83
	v_mul_f32_e32 v84, 0xbfb8aa3b, v84
	v_mul_f32_e32 v85, 0xbfb8aa3b, v85
	v_mul_f32_e32 v86, 0xbfb8aa3b, v86
	v_mul_f32_e32 v87, 0xbfb8aa3b, v87
	v_mul_f32_e32 v80, 0xbfb8aa3b, v80
	v_mul_f32_e32 v81, 0xbfb8aa3b, v81
	v_mul_f32_e32 v82, 0xbfb8aa3b, v82
	v_mul_f32_e32 v83, 0xbfb8aa3b, v83
	v_exp_f32_e32 v84, v84
	v_exp_f32_e32 v85, v85
	v_exp_f32_e32 v86, v86
	v_exp_f32_e32 v87, v87
	v_exp_f32_e32 v80, v80
	v_exp_f32_e32 v81, v81
	v_exp_f32_e32 v82, v82
	v_exp_f32_e32 v83, v83
	v_add_f32_e32 v84, 1.0, v84
	v_add_f32_e32 v85, 1.0, v85
	v_add_f32_e32 v86, 1.0, v86
	v_add_f32_e32 v87, 1.0, v87
	v_add_f32_e32 v80, 1.0, v80
	v_add_f32_e32 v81, 1.0, v81
	v_add_f32_e32 v82, 1.0, v82
	v_add_f32_e32 v83, 1.0, v83
	v_rcp_f32_e32 v84, v84
	v_rcp_f32_e32 v85, v85
	v_rcp_f32_e32 v86, v86
	v_rcp_f32_e32 v87, v87
	v_rcp_f32_e32 v80, v80
	v_rcp_f32_e32 v81, v81
	v_rcp_f32_e32 v82, v82
	v_rcp_f32_e32 v83, v83
	v_lshlrev_b32_e32 v148, 16, v222
	v_lshlrev_b32_e32 v149, 16, v226
	v_and_b32_e32 v150, 0xffff0000, v222
	v_and_b32_e32 v151, 0xffff0000, v226
	v_fma_f32 v84, v84, v149, v148
	v_fma_f32 v85, v85, v151, v150
	v_lshlrev_b32_e32 v152, 16, v223
	v_lshlrev_b32_e32 v153, 16, v227
	v_and_b32_e32 v154, 0xffff0000, v223
	v_and_b32_e32 v155, 0xffff0000, v227
	v_fma_f32 v86, v86, v153, v152
	v_fma_f32 v87, v87, v155, v154
	v_lshlrev_b32_e32 v148, 16, v224
	v_lshlrev_b32_e32 v149, 16, v228
	v_and_b32_e32 v150, 0xffff0000, v224
	v_and_b32_e32 v151, 0xffff0000, v228
	v_fma_f32 v80, v80, v149, v148
	v_fma_f32 v81, v81, v151, v150
	v_lshlrev_b32_e32 v152, 16, v225
	v_lshlrev_b32_e32 v153, 16, v229
	v_and_b32_e32 v154, 0xffff0000, v225
	v_and_b32_e32 v155, 0xffff0000, v229
	v_fma_f32 v82, v82, v153, v152
	v_fma_f32 v83, v83, v155, v154
	v_cvt_pk_bf16_f32 v222, v84, v85
	v_cvt_pk_bf16_f32 v223, v86, v87
	v_cvt_pk_bf16_f32 v224, v80, v81
	v_cvt_pk_bf16_f32 v225, v82, v83
	s_add_u32 s28, s0, 0x10000
	s_addc_u32 s29, s1, 0
	global_store_dwordx4 v136, v[222:225], s[28:29] offset:256 nt
	s_add_u32 s28, s0, 0x48000
	s_addc_u32 s29, s1, 0
	s_add_u32 s100, s26, 0x48000
	s_addc_u32 s101, s27, 0
	global_load_dwordx4 v[84:87], v136, s[28:29] offset:256
	global_load_dwordx4 v[80:83], v136, s[100:101] offset:256
	v_lshlrev_b32_e32 v148, 16, v222
	v_lshlrev_b32_e32 v149, 16, v223
	v_and_b32_e32 v150, 0xffff0000, v222
	v_and_b32_e32 v151, 0xffff0000, v223
	v_lshlrev_b32_e32 v152, 16, v224
	v_lshlrev_b32_e32 v153, 16, v225
	v_and_b32_e32 v154, 0xffff0000, v224
	v_and_b32_e32 v155, 0xffff0000, v225
	v_pk_mul_f32 v[150:151], v[150:151], v[150:151]
	v_pk_mul_f32 v[154:155], v[154:155], v[154:155]
	v_pk_fma_f32 v[148:149], v[148:149], v[148:149], v[150:151]
	v_pk_fma_f32 v[152:153], v[152:153], v[152:153], v[154:155]
	s_nop 0
	v_add_f32_e32 v148, v148, v149
	v_add_f32_e32 v152, v152, v153
	v_add_f32_e32 v158, v158, v148
	v_add_f32_e32 v158, v158, v152
	s_waitcnt vmcnt(15)
	v_permlane16_swap_b32_e32 v76, v72
	v_permlane16_swap_b32_e32 v77, v73
	v_permlane16_swap_b32_e32 v78, v74
	v_permlane16_swap_b32_e32 v79, v75
	v_mul_f32_e32 v76, 0xbfb8aa3b, v76
	v_mul_f32_e32 v77, 0xbfb8aa3b, v77
	v_mul_f32_e32 v78, 0xbfb8aa3b, v78
	v_mul_f32_e32 v79, 0xbfb8aa3b, v79
	v_mul_f32_e32 v72, 0xbfb8aa3b, v72
	v_mul_f32_e32 v73, 0xbfb8aa3b, v73
	v_mul_f32_e32 v74, 0xbfb8aa3b, v74
	v_mul_f32_e32 v75, 0xbfb8aa3b, v75
	v_exp_f32_e32 v76, v76
	v_exp_f32_e32 v77, v77
	v_exp_f32_e32 v78, v78
	v_exp_f32_e32 v79, v79
	v_exp_f32_e32 v72, v72
	v_exp_f32_e32 v73, v73
	v_exp_f32_e32 v74, v74
	v_exp_f32_e32 v75, v75
	v_add_f32_e32 v76, 1.0, v76
	v_add_f32_e32 v77, 1.0, v77
	v_add_f32_e32 v78, 1.0, v78
	v_add_f32_e32 v79, 1.0, v79
	v_add_f32_e32 v72, 1.0, v72
	v_add_f32_e32 v73, 1.0, v73
	v_add_f32_e32 v74, 1.0, v74
	v_add_f32_e32 v75, 1.0, v75
	v_rcp_f32_e32 v76, v76
	v_rcp_f32_e32 v77, v77
	v_rcp_f32_e32 v78, v78
	v_rcp_f32_e32 v79, v79
	v_rcp_f32_e32 v72, v72
	v_rcp_f32_e32 v73, v73
	v_rcp_f32_e32 v74, v74
	v_rcp_f32_e32 v75, v75
	v_lshlrev_b32_e32 v148, 16, v126
	v_lshlrev_b32_e32 v149, 16, v122
	v_and_b32_e32 v150, 0xffff0000, v126
	v_and_b32_e32 v151, 0xffff0000, v122
	v_fma_f32 v76, v76, v149, v148
	v_fma_f32 v77, v77, v151, v150
	v_lshlrev_b32_e32 v152, 16, v127
	v_lshlrev_b32_e32 v153, 16, v123
	v_and_b32_e32 v154, 0xffff0000, v127
	v_and_b32_e32 v155, 0xffff0000, v123
	v_fma_f32 v78, v78, v153, v152
	v_fma_f32 v79, v79, v155, v154
	v_lshlrev_b32_e32 v148, 16, v128
	v_lshlrev_b32_e32 v149, 16, v124
	v_and_b32_e32 v150, 0xffff0000, v128
	v_and_b32_e32 v151, 0xffff0000, v124
	v_fma_f32 v72, v72, v149, v148
	v_fma_f32 v73, v73, v151, v150
	v_lshlrev_b32_e32 v152, 16, v129
	v_lshlrev_b32_e32 v153, 16, v125
	v_and_b32_e32 v154, 0xffff0000, v129
	v_and_b32_e32 v155, 0xffff0000, v125
	v_fma_f32 v74, v74, v153, v152
	v_fma_f32 v75, v75, v155, v154
	v_cvt_pk_bf16_f32 v126, v76, v77
	v_cvt_pk_bf16_f32 v127, v78, v79
	v_cvt_pk_bf16_f32 v128, v72, v73
	v_cvt_pk_bf16_f32 v129, v74, v75
	s_add_u32 s28, s0, 0x18000
	s_addc_u32 s29, s1, 0
	global_store_dwordx4 v136, v[126:129], s[28:29] nt
	s_add_u32 s28, s0, 0x50000
	s_addc_u32 s29, s1, 0
	s_add_u32 s100, s26, 0x50000
	s_addc_u32 s101, s27, 0
	global_load_dwordx4 v[76:79], v136, s[28:29]
	global_load_dwordx4 v[72:75], v136, s[100:101]
	v_lshlrev_b32_e32 v148, 16, v126
	v_lshlrev_b32_e32 v149, 16, v127
	v_and_b32_e32 v150, 0xffff0000, v126
	v_and_b32_e32 v151, 0xffff0000, v127
	v_lshlrev_b32_e32 v152, 16, v128
	v_lshlrev_b32_e32 v153, 16, v129
	v_and_b32_e32 v154, 0xffff0000, v128
	v_and_b32_e32 v155, 0xffff0000, v129
	v_pk_mul_f32 v[150:151], v[150:151], v[150:151]
	v_pk_mul_f32 v[154:155], v[154:155], v[154:155]
	v_pk_fma_f32 v[148:149], v[148:149], v[148:149], v[150:151]
	v_pk_fma_f32 v[152:153], v[152:153], v[152:153], v[154:155]
	s_nop 0
	v_add_f32_e32 v148, v148, v149
	v_add_f32_e32 v152, v152, v153
	v_add_f32_e32 v159, v148, v152
	s_waitcnt vmcnt(15)
	v_permlane16_swap_b32_e32 v68, v64
	v_permlane16_swap_b32_e32 v69, v65
	v_permlane16_swap_b32_e32 v70, v66
	v_permlane16_swap_b32_e32 v71, v67
	v_mul_f32_e32 v68, 0xbfb8aa3b, v68
	v_mul_f32_e32 v69, 0xbfb8aa3b, v69
	v_mul_f32_e32 v70, 0xbfb8aa3b, v70
	v_mul_f32_e32 v71, 0xbfb8aa3b, v71
	v_mul_f32_e32 v64, 0xbfb8aa3b, v64
	v_mul_f32_e32 v65, 0xbfb8aa3b, v65
	v_mul_f32_e32 v66, 0xbfb8aa3b, v66
	v_mul_f32_e32 v67, 0xbfb8aa3b, v67
	v_exp_f32_e32 v68, v68
	v_exp_f32_e32 v69, v69
	v_exp_f32_e32 v70, v70
	v_exp_f32_e32 v71, v71
	v_exp_f32_e32 v64, v64
	v_exp_f32_e32 v65, v65
	v_exp_f32_e32 v66, v66
	v_exp_f32_e32 v67, v67
	v_add_f32_e32 v68, 1.0, v68
	v_add_f32_e32 v69, 1.0, v69
	v_add_f32_e32 v70, 1.0, v70
	v_add_f32_e32 v71, 1.0, v71
	v_add_f32_e32 v64, 1.0, v64
	v_add_f32_e32 v65, 1.0, v65
	v_add_f32_e32 v66, 1.0, v66
	v_add_f32_e32 v67, 1.0, v67
	v_rcp_f32_e32 v68, v68
	v_rcp_f32_e32 v69, v69
	v_rcp_f32_e32 v70, v70
	v_rcp_f32_e32 v71, v71
	v_rcp_f32_e32 v64, v64
	v_rcp_f32_e32 v65, v65
	v_rcp_f32_e32 v66, v66
	v_rcp_f32_e32 v67, v67
	v_lshlrev_b32_e32 v148, 16, v118
	v_lshlrev_b32_e32 v149, 16, v114
	v_and_b32_e32 v150, 0xffff0000, v118
	v_and_b32_e32 v151, 0xffff0000, v114
	v_fma_f32 v68, v68, v149, v148
	v_fma_f32 v69, v69, v151, v150
	v_lshlrev_b32_e32 v152, 16, v119
	v_lshlrev_b32_e32 v153, 16, v115
	v_and_b32_e32 v154, 0xffff0000, v119
	v_and_b32_e32 v155, 0xffff0000, v115
	v_fma_f32 v70, v70, v153, v152
	v_fma_f32 v71, v71, v155, v154
	v_lshlrev_b32_e32 v148, 16, v120
	v_lshlrev_b32_e32 v149, 16, v116
	v_and_b32_e32 v150, 0xffff0000, v120
	v_and_b32_e32 v151, 0xffff0000, v116
	v_fma_f32 v64, v64, v149, v148
	v_fma_f32 v65, v65, v151, v150
	v_lshlrev_b32_e32 v152, 16, v121
	v_lshlrev_b32_e32 v153, 16, v117
	v_and_b32_e32 v154, 0xffff0000, v121
	v_and_b32_e32 v155, 0xffff0000, v117
	v_fma_f32 v66, v66, v153, v152
	v_fma_f32 v67, v67, v155, v154
	v_cvt_pk_bf16_f32 v118, v68, v69
	v_cvt_pk_bf16_f32 v119, v70, v71
	v_cvt_pk_bf16_f32 v120, v64, v65
	v_cvt_pk_bf16_f32 v121, v66, v67
	s_add_u32 s28, s0, 0x18000
	s_addc_u32 s29, s1, 0
	global_store_dwordx4 v136, v[118:121], s[28:29] offset:256 nt
	s_add_u32 s28, s0, 0x50000
	s_addc_u32 s29, s1, 0
	s_add_u32 s100, s26, 0x50000
	s_addc_u32 s101, s27, 0
	global_load_dwordx4 v[68:71], v136, s[28:29] offset:256
	global_load_dwordx4 v[64:67], v136, s[100:101] offset:256
	v_lshlrev_b32_e32 v148, 16, v118
	v_lshlrev_b32_e32 v149, 16, v119
	v_and_b32_e32 v150, 0xffff0000, v118
	v_and_b32_e32 v151, 0xffff0000, v119
	v_lshlrev_b32_e32 v152, 16, v120
	v_lshlrev_b32_e32 v153, 16, v121
	v_and_b32_e32 v154, 0xffff0000, v120
	v_and_b32_e32 v155, 0xffff0000, v121
	v_pk_mul_f32 v[150:151], v[150:151], v[150:151]
	v_pk_mul_f32 v[154:155], v[154:155], v[154:155]
	v_pk_fma_f32 v[148:149], v[148:149], v[148:149], v[150:151]
	v_pk_fma_f32 v[152:153], v[152:153], v[152:153], v[154:155]
	s_nop 0
	v_add_f32_e32 v148, v148, v149
	v_add_f32_e32 v152, v152, v153
	v_add_f32_e32 v159, v159, v148
	v_add_f32_e32 v159, v159, v152
	ds_bpermute_b32 v148, v137, v156
	ds_bpermute_b32 v149, v137, v157
	ds_bpermute_b32 v150, v137, v158
	ds_bpermute_b32 v151, v137, v159
	s_waitcnt lgkmcnt(0)
	v_add_f32_e32 v156, v156, v148
	v_add_f32_e32 v157, v157, v149
	v_add_f32_e32 v158, v158, v150
	v_add_f32_e32 v159, v159, v151
	ds_bpermute_b32 v148, v138, v156
	ds_bpermute_b32 v149, v138, v157
	ds_bpermute_b32 v150, v138, v158
	ds_bpermute_b32 v151, v138, v159
	s_waitcnt lgkmcnt(0)
	v_add_f32_e32 v156, v156, v148
	v_add_f32_e32 v157, v157, v149
	v_add_f32_e32 v158, v158, v150
	v_add_f32_e32 v159, v159, v151
	s_and_saveexec_b64 vcc, s[4:5]
	ds_write_b32 v146, v156
	ds_write_b32 v146, v157 offset:256
	ds_write_b32 v146, v158 offset:512
	ds_write_b32 v146, v159 offset:768
	s_or_b64 exec, exec, vcc
	s_waitcnt vmcnt(15)
	v_permlane16_swap_b32_e32 v60, v56
	v_permlane16_swap_b32_e32 v61, v57
	v_permlane16_swap_b32_e32 v62, v58
	v_permlane16_swap_b32_e32 v63, v59
	v_mul_f32_e32 v60, 0xbfb8aa3b, v60
	v_mul_f32_e32 v61, 0xbfb8aa3b, v61
	v_mul_f32_e32 v62, 0xbfb8aa3b, v62
	v_mul_f32_e32 v63, 0xbfb8aa3b, v63
	v_mul_f32_e32 v56, 0xbfb8aa3b, v56
	v_mul_f32_e32 v57, 0xbfb8aa3b, v57
	v_mul_f32_e32 v58, 0xbfb8aa3b, v58
	v_mul_f32_e32 v59, 0xbfb8aa3b, v59
	v_exp_f32_e32 v60, v60
	v_exp_f32_e32 v61, v61
	v_exp_f32_e32 v62, v62
	v_exp_f32_e32 v63, v63
	v_exp_f32_e32 v56, v56
	v_exp_f32_e32 v57, v57
	v_exp_f32_e32 v58, v58
	v_exp_f32_e32 v59, v59
	v_add_f32_e32 v60, 1.0, v60
	v_add_f32_e32 v61, 1.0, v61
	v_add_f32_e32 v62, 1.0, v62
	v_add_f32_e32 v63, 1.0, v63
	v_add_f32_e32 v56, 1.0, v56
	v_add_f32_e32 v57, 1.0, v57
	v_add_f32_e32 v58, 1.0, v58
	v_add_f32_e32 v59, 1.0, v59
	v_rcp_f32_e32 v60, v60
	v_rcp_f32_e32 v61, v61
	v_rcp_f32_e32 v62, v62
	v_rcp_f32_e32 v63, v63
	v_rcp_f32_e32 v56, v56
	v_rcp_f32_e32 v57, v57
	v_rcp_f32_e32 v58, v58
	v_rcp_f32_e32 v59, v59
	v_lshlrev_b32_e32 v148, 16, v110
	v_lshlrev_b32_e32 v149, 16, v106
	v_and_b32_e32 v150, 0xffff0000, v110
	v_and_b32_e32 v151, 0xffff0000, v106
	v_fma_f32 v60, v60, v149, v148
	v_fma_f32 v61, v61, v151, v150
	v_lshlrev_b32_e32 v152, 16, v111
	v_lshlrev_b32_e32 v153, 16, v107
	v_and_b32_e32 v154, 0xffff0000, v111
	v_and_b32_e32 v155, 0xffff0000, v107
	v_fma_f32 v62, v62, v153, v152
	v_fma_f32 v63, v63, v155, v154
	v_lshlrev_b32_e32 v148, 16, v112
	v_lshlrev_b32_e32 v149, 16, v108
	v_and_b32_e32 v150, 0xffff0000, v112
	v_and_b32_e32 v151, 0xffff0000, v108
	v_fma_f32 v56, v56, v149, v148
	v_fma_f32 v57, v57, v151, v150
	v_lshlrev_b32_e32 v152, 16, v113
	v_lshlrev_b32_e32 v153, 16, v109
	v_and_b32_e32 v154, 0xffff0000, v113
	v_and_b32_e32 v155, 0xffff0000, v109
	v_fma_f32 v58, v58, v153, v152
	v_fma_f32 v59, v59, v155, v154
	v_cvt_pk_bf16_f32 v110, v60, v61
	v_cvt_pk_bf16_f32 v111, v62, v63
	v_cvt_pk_bf16_f32 v112, v56, v57
	v_cvt_pk_bf16_f32 v113, v58, v59
	s_add_u32 s28, s0, 0x40000
	s_addc_u32 s29, s1, 0
	global_store_dwordx4 v136, v[110:113], s[28:29] nt
	s_add_u32 s28, s0, 0x58000
	s_addc_u32 s29, s1, 0
	s_add_u32 s100, s26, 0x58000
	s_addc_u32 s101, s27, 0
	global_load_dwordx4 v[60:63], v136, s[28:29]
	global_load_dwordx4 v[56:59], v136, s[100:101]
	v_lshlrev_b32_e32 v148, 16, v110
	v_lshlrev_b32_e32 v149, 16, v111
	v_and_b32_e32 v150, 0xffff0000, v110
	v_and_b32_e32 v151, 0xffff0000, v111
	v_lshlrev_b32_e32 v152, 16, v112
	v_lshlrev_b32_e32 v153, 16, v113
	v_and_b32_e32 v154, 0xffff0000, v112
	v_and_b32_e32 v155, 0xffff0000, v113
	v_pk_mul_f32 v[150:151], v[150:151], v[150:151]
	v_pk_mul_f32 v[154:155], v[154:155], v[154:155]
	v_pk_fma_f32 v[148:149], v[148:149], v[148:149], v[150:151]
	v_pk_fma_f32 v[152:153], v[152:153], v[152:153], v[154:155]
	s_nop 0
	v_add_f32_e32 v148, v148, v149
	v_add_f32_e32 v152, v152, v153
	v_add_f32_e32 v156, v148, v152
	s_waitcnt vmcnt(15)
	v_permlane16_swap_b32_e32 v52, v48
	v_permlane16_swap_b32_e32 v53, v49
	v_permlane16_swap_b32_e32 v54, v50
	v_permlane16_swap_b32_e32 v55, v51
	v_mul_f32_e32 v52, 0xbfb8aa3b, v52
	v_mul_f32_e32 v53, 0xbfb8aa3b, v53
	v_mul_f32_e32 v54, 0xbfb8aa3b, v54
	v_mul_f32_e32 v55, 0xbfb8aa3b, v55
	v_mul_f32_e32 v48, 0xbfb8aa3b, v48
	v_mul_f32_e32 v49, 0xbfb8aa3b, v49
	v_mul_f32_e32 v50, 0xbfb8aa3b, v50
	v_mul_f32_e32 v51, 0xbfb8aa3b, v51
	v_exp_f32_e32 v52, v52
	v_exp_f32_e32 v53, v53
	v_exp_f32_e32 v54, v54
	v_exp_f32_e32 v55, v55
	v_exp_f32_e32 v48, v48
	v_exp_f32_e32 v49, v49
	v_exp_f32_e32 v50, v50
	v_exp_f32_e32 v51, v51
	v_add_f32_e32 v52, 1.0, v52
	v_add_f32_e32 v53, 1.0, v53
	v_add_f32_e32 v54, 1.0, v54
	v_add_f32_e32 v55, 1.0, v55
	v_add_f32_e32 v48, 1.0, v48
	v_add_f32_e32 v49, 1.0, v49
	v_add_f32_e32 v50, 1.0, v50
	v_add_f32_e32 v51, 1.0, v51
	v_rcp_f32_e32 v52, v52
	v_rcp_f32_e32 v53, v53
	v_rcp_f32_e32 v54, v54
	v_rcp_f32_e32 v55, v55
	v_rcp_f32_e32 v48, v48
	v_rcp_f32_e32 v49, v49
	v_rcp_f32_e32 v50, v50
	v_rcp_f32_e32 v51, v51
	v_lshlrev_b32_e32 v148, 16, v102
	v_lshlrev_b32_e32 v149, 16, v98
	v_and_b32_e32 v150, 0xffff0000, v102
	v_and_b32_e32 v151, 0xffff0000, v98
	v_fma_f32 v52, v52, v149, v148
	v_fma_f32 v53, v53, v151, v150
	v_lshlrev_b32_e32 v152, 16, v103
	v_lshlrev_b32_e32 v153, 16, v99
	v_and_b32_e32 v154, 0xffff0000, v103
	v_and_b32_e32 v155, 0xffff0000, v99
	v_fma_f32 v54, v54, v153, v152
	v_fma_f32 v55, v55, v155, v154
	v_lshlrev_b32_e32 v148, 16, v104
	v_lshlrev_b32_e32 v149, 16, v100
	v_and_b32_e32 v150, 0xffff0000, v104
	v_and_b32_e32 v151, 0xffff0000, v100
	v_fma_f32 v48, v48, v149, v148
	v_fma_f32 v49, v49, v151, v150
	v_lshlrev_b32_e32 v152, 16, v105
	v_lshlrev_b32_e32 v153, 16, v101
	v_and_b32_e32 v154, 0xffff0000, v105
	v_and_b32_e32 v155, 0xffff0000, v101
	v_fma_f32 v50, v50, v153, v152
	v_fma_f32 v51, v51, v155, v154
	v_cvt_pk_bf16_f32 v102, v52, v53
	v_cvt_pk_bf16_f32 v103, v54, v55
	v_cvt_pk_bf16_f32 v104, v48, v49
	v_cvt_pk_bf16_f32 v105, v50, v51
	s_add_u32 s28, s0, 0x40000
	s_addc_u32 s29, s1, 0
	global_store_dwordx4 v136, v[102:105], s[28:29] offset:256 nt
	s_add_u32 s28, s0, 0x58000
	s_addc_u32 s29, s1, 0
	s_add_u32 s100, s26, 0x58000
	s_addc_u32 s101, s27, 0
	global_load_dwordx4 v[52:55], v136, s[28:29] offset:256
	global_load_dwordx4 v[48:51], v136, s[100:101] offset:256
	v_lshlrev_b32_e32 v148, 16, v102
	v_lshlrev_b32_e32 v149, 16, v103
	v_and_b32_e32 v150, 0xffff0000, v102
	v_and_b32_e32 v151, 0xffff0000, v103
	v_lshlrev_b32_e32 v152, 16, v104
	v_lshlrev_b32_e32 v153, 16, v105
	v_and_b32_e32 v154, 0xffff0000, v104
	v_and_b32_e32 v155, 0xffff0000, v105
	v_pk_mul_f32 v[150:151], v[150:151], v[150:151]
	v_pk_mul_f32 v[154:155], v[154:155], v[154:155]
	v_pk_fma_f32 v[148:149], v[148:149], v[148:149], v[150:151]
	v_pk_fma_f32 v[152:153], v[152:153], v[152:153], v[154:155]
	s_nop 0
	v_add_f32_e32 v148, v148, v149
	v_add_f32_e32 v152, v152, v153
	v_add_f32_e32 v156, v156, v148
	v_add_f32_e32 v156, v156, v152
	s_waitcnt vmcnt(15)
	v_permlane16_swap_b32_e32 v44, v40
	v_permlane16_swap_b32_e32 v45, v41
	v_permlane16_swap_b32_e32 v46, v42
	v_permlane16_swap_b32_e32 v47, v43
	v_mul_f32_e32 v44, 0xbfb8aa3b, v44
	v_mul_f32_e32 v45, 0xbfb8aa3b, v45
	v_mul_f32_e32 v46, 0xbfb8aa3b, v46
	v_mul_f32_e32 v47, 0xbfb8aa3b, v47
	v_mul_f32_e32 v40, 0xbfb8aa3b, v40
	v_mul_f32_e32 v41, 0xbfb8aa3b, v41
	v_mul_f32_e32 v42, 0xbfb8aa3b, v42
	v_mul_f32_e32 v43, 0xbfb8aa3b, v43
	v_exp_f32_e32 v44, v44
	v_exp_f32_e32 v45, v45
	v_exp_f32_e32 v46, v46
	v_exp_f32_e32 v47, v47
	v_exp_f32_e32 v40, v40
	v_exp_f32_e32 v41, v41
	v_exp_f32_e32 v42, v42
	v_exp_f32_e32 v43, v43
	v_add_f32_e32 v44, 1.0, v44
	v_add_f32_e32 v45, 1.0, v45
	v_add_f32_e32 v46, 1.0, v46
	v_add_f32_e32 v47, 1.0, v47
	v_add_f32_e32 v40, 1.0, v40
	v_add_f32_e32 v41, 1.0, v41
	v_add_f32_e32 v42, 1.0, v42
	v_add_f32_e32 v43, 1.0, v43
	v_rcp_f32_e32 v44, v44
	v_rcp_f32_e32 v45, v45
	v_rcp_f32_e32 v46, v46
	v_rcp_f32_e32 v47, v47
	v_rcp_f32_e32 v40, v40
	v_rcp_f32_e32 v41, v41
	v_rcp_f32_e32 v42, v42
	v_rcp_f32_e32 v43, v43
	v_lshlrev_b32_e32 v148, 16, v92
	v_lshlrev_b32_e32 v149, 16, v88
	v_and_b32_e32 v150, 0xffff0000, v92
	v_and_b32_e32 v151, 0xffff0000, v88
	v_fma_f32 v44, v44, v149, v148
	v_fma_f32 v45, v45, v151, v150
	v_lshlrev_b32_e32 v152, 16, v93
	v_lshlrev_b32_e32 v153, 16, v89
	v_and_b32_e32 v154, 0xffff0000, v93
	v_and_b32_e32 v155, 0xffff0000, v89
	v_fma_f32 v46, v46, v153, v152
	v_fma_f32 v47, v47, v155, v154
	v_lshlrev_b32_e32 v148, 16, v94
	v_lshlrev_b32_e32 v149, 16, v90
	v_and_b32_e32 v150, 0xffff0000, v94
	v_and_b32_e32 v151, 0xffff0000, v90
	v_fma_f32 v40, v40, v149, v148
	v_fma_f32 v41, v41, v151, v150
	v_lshlrev_b32_e32 v152, 16, v95
	v_lshlrev_b32_e32 v153, 16, v91
	v_and_b32_e32 v154, 0xffff0000, v95
	v_and_b32_e32 v155, 0xffff0000, v91
	v_fma_f32 v42, v42, v153, v152
	v_fma_f32 v43, v43, v155, v154
	v_cvt_pk_bf16_f32 v92, v44, v45
	v_cvt_pk_bf16_f32 v93, v46, v47
	v_cvt_pk_bf16_f32 v94, v40, v41
	v_cvt_pk_bf16_f32 v95, v42, v43
	s_add_u32 s28, s0, 0x48000
	s_addc_u32 s29, s1, 0
	global_store_dwordx4 v136, v[92:95], s[28:29] nt
	v_lshlrev_b32_e32 v148, 16, v92
	v_lshlrev_b32_e32 v149, 16, v93
	v_and_b32_e32 v150, 0xffff0000, v92
	v_and_b32_e32 v151, 0xffff0000, v93
	v_lshlrev_b32_e32 v152, 16, v94
	v_lshlrev_b32_e32 v153, 16, v95
	v_and_b32_e32 v154, 0xffff0000, v94
	v_and_b32_e32 v155, 0xffff0000, v95
	v_pk_mul_f32 v[150:151], v[150:151], v[150:151]
	v_pk_mul_f32 v[154:155], v[154:155], v[154:155]
	v_pk_fma_f32 v[148:149], v[148:149], v[148:149], v[150:151]
	v_pk_fma_f32 v[152:153], v[152:153], v[152:153], v[154:155]
	s_nop 0
	v_add_f32_e32 v148, v148, v149
	v_add_f32_e32 v152, v152, v153
	v_add_f32_e32 v157, v148, v152
	s_waitcnt vmcnt(13)
	v_permlane16_swap_b32_e32 v36, v32
	v_permlane16_swap_b32_e32 v37, v33
	v_permlane16_swap_b32_e32 v38, v34
	v_permlane16_swap_b32_e32 v39, v35
	v_mul_f32_e32 v36, 0xbfb8aa3b, v36
	v_mul_f32_e32 v37, 0xbfb8aa3b, v37
	v_mul_f32_e32 v38, 0xbfb8aa3b, v38
	v_mul_f32_e32 v39, 0xbfb8aa3b, v39
	v_mul_f32_e32 v32, 0xbfb8aa3b, v32
	v_mul_f32_e32 v33, 0xbfb8aa3b, v33
	v_mul_f32_e32 v34, 0xbfb8aa3b, v34
	v_mul_f32_e32 v35, 0xbfb8aa3b, v35
	v_exp_f32_e32 v36, v36
	v_exp_f32_e32 v37, v37
	v_exp_f32_e32 v38, v38
	v_exp_f32_e32 v39, v39
	v_exp_f32_e32 v32, v32
	v_exp_f32_e32 v33, v33
	v_exp_f32_e32 v34, v34
	v_exp_f32_e32 v35, v35
	v_add_f32_e32 v36, 1.0, v36
	v_add_f32_e32 v37, 1.0, v37
	v_add_f32_e32 v38, 1.0, v38
	v_add_f32_e32 v39, 1.0, v39
	v_add_f32_e32 v32, 1.0, v32
	v_add_f32_e32 v33, 1.0, v33
	v_add_f32_e32 v34, 1.0, v34
	v_add_f32_e32 v35, 1.0, v35
	v_rcp_f32_e32 v36, v36
	v_rcp_f32_e32 v37, v37
	v_rcp_f32_e32 v38, v38
	v_rcp_f32_e32 v39, v39
	v_rcp_f32_e32 v32, v32
	v_rcp_f32_e32 v33, v33
	v_rcp_f32_e32 v34, v34
	v_rcp_f32_e32 v35, v35
	v_lshlrev_b32_e32 v148, 16, v84
	v_lshlrev_b32_e32 v149, 16, v80
	v_and_b32_e32 v150, 0xffff0000, v84
	v_and_b32_e32 v151, 0xffff0000, v80
	v_fma_f32 v36, v36, v149, v148
	v_fma_f32 v37, v37, v151, v150
	v_lshlrev_b32_e32 v152, 16, v85
	v_lshlrev_b32_e32 v153, 16, v81
	v_and_b32_e32 v154, 0xffff0000, v85
	v_and_b32_e32 v155, 0xffff0000, v81
	v_fma_f32 v38, v38, v153, v152
	v_fma_f32 v39, v39, v155, v154
	v_lshlrev_b32_e32 v148, 16, v86
	v_lshlrev_b32_e32 v149, 16, v82
	v_and_b32_e32 v150, 0xffff0000, v86
	v_and_b32_e32 v151, 0xffff0000, v82
	v_fma_f32 v32, v32, v149, v148
	v_fma_f32 v33, v33, v151, v150
	v_lshlrev_b32_e32 v152, 16, v87
	v_lshlrev_b32_e32 v153, 16, v83
	v_and_b32_e32 v154, 0xffff0000, v87
	v_and_b32_e32 v155, 0xffff0000, v83
	v_fma_f32 v34, v34, v153, v152
	v_fma_f32 v35, v35, v155, v154
	v_cvt_pk_bf16_f32 v84, v36, v37
	v_cvt_pk_bf16_f32 v85, v38, v39
	v_cvt_pk_bf16_f32 v86, v32, v33
	v_cvt_pk_bf16_f32 v87, v34, v35
	s_add_u32 s28, s0, 0x48000
	s_addc_u32 s29, s1, 0
	global_store_dwordx4 v136, v[84:87], s[28:29] offset:256 nt
	v_lshlrev_b32_e32 v148, 16, v84
	v_lshlrev_b32_e32 v149, 16, v85
	v_and_b32_e32 v150, 0xffff0000, v84
	v_and_b32_e32 v151, 0xffff0000, v85
	v_lshlrev_b32_e32 v152, 16, v86
	v_lshlrev_b32_e32 v153, 16, v87
	v_and_b32_e32 v154, 0xffff0000, v86
	v_and_b32_e32 v155, 0xffff0000, v87
	v_pk_mul_f32 v[150:151], v[150:151], v[150:151]
	v_pk_mul_f32 v[154:155], v[154:155], v[154:155]
	v_pk_fma_f32 v[148:149], v[148:149], v[148:149], v[150:151]
	v_pk_fma_f32 v[152:153], v[152:153], v[152:153], v[154:155]
	s_nop 0
	v_add_f32_e32 v148, v148, v149
	v_add_f32_e32 v152, v152, v153
	v_add_f32_e32 v157, v157, v148
	v_add_f32_e32 v157, v157, v152
	s_waitcnt vmcnt(11)
	v_permlane16_swap_b32_e32 v28, v24
	v_permlane16_swap_b32_e32 v29, v25
	v_permlane16_swap_b32_e32 v30, v26
	v_permlane16_swap_b32_e32 v31, v27
	v_mul_f32_e32 v28, 0xbfb8aa3b, v28
	v_mul_f32_e32 v29, 0xbfb8aa3b, v29
	v_mul_f32_e32 v30, 0xbfb8aa3b, v30
	v_mul_f32_e32 v31, 0xbfb8aa3b, v31
	v_mul_f32_e32 v24, 0xbfb8aa3b, v24
	v_mul_f32_e32 v25, 0xbfb8aa3b, v25
	v_mul_f32_e32 v26, 0xbfb8aa3b, v26
	v_mul_f32_e32 v27, 0xbfb8aa3b, v27
	v_exp_f32_e32 v28, v28
	v_exp_f32_e32 v29, v29
	v_exp_f32_e32 v30, v30
	v_exp_f32_e32 v31, v31
	v_exp_f32_e32 v24, v24
	v_exp_f32_e32 v25, v25
	v_exp_f32_e32 v26, v26
	v_exp_f32_e32 v27, v27
	v_add_f32_e32 v28, 1.0, v28
	v_add_f32_e32 v29, 1.0, v29
	v_add_f32_e32 v30, 1.0, v30
	v_add_f32_e32 v31, 1.0, v31
	v_add_f32_e32 v24, 1.0, v24
	v_add_f32_e32 v25, 1.0, v25
	v_add_f32_e32 v26, 1.0, v26
	v_add_f32_e32 v27, 1.0, v27
	v_rcp_f32_e32 v28, v28
	v_rcp_f32_e32 v29, v29
	v_rcp_f32_e32 v30, v30
	v_rcp_f32_e32 v31, v31
	v_rcp_f32_e32 v24, v24
	v_rcp_f32_e32 v25, v25
	v_rcp_f32_e32 v26, v26
	v_rcp_f32_e32 v27, v27
	v_lshlrev_b32_e32 v148, 16, v76
	v_lshlrev_b32_e32 v149, 16, v72
	v_and_b32_e32 v150, 0xffff0000, v76
	v_and_b32_e32 v151, 0xffff0000, v72
	v_fma_f32 v28, v28, v149, v148
	v_fma_f32 v29, v29, v151, v150
	v_lshlrev_b32_e32 v152, 16, v77
	v_lshlrev_b32_e32 v153, 16, v73
	v_and_b32_e32 v154, 0xffff0000, v77
	v_and_b32_e32 v155, 0xffff0000, v73
	v_fma_f32 v30, v30, v153, v152
	v_fma_f32 v31, v31, v155, v154
	v_lshlrev_b32_e32 v148, 16, v78
	v_lshlrev_b32_e32 v149, 16, v74
	v_and_b32_e32 v150, 0xffff0000, v78
	v_and_b32_e32 v151, 0xffff0000, v74
	v_fma_f32 v24, v24, v149, v148
	v_fma_f32 v25, v25, v151, v150
	v_lshlrev_b32_e32 v152, 16, v79
	v_lshlrev_b32_e32 v153, 16, v75
	v_and_b32_e32 v154, 0xffff0000, v79
	v_and_b32_e32 v155, 0xffff0000, v75
	v_fma_f32 v26, v26, v153, v152
	v_fma_f32 v27, v27, v155, v154
	v_cvt_pk_bf16_f32 v76, v28, v29
	v_cvt_pk_bf16_f32 v77, v30, v31
	v_cvt_pk_bf16_f32 v78, v24, v25
	v_cvt_pk_bf16_f32 v79, v26, v27
	s_add_u32 s28, s0, 0x50000
	s_addc_u32 s29, s1, 0
	global_store_dwordx4 v136, v[76:79], s[28:29] nt
	v_lshlrev_b32_e32 v148, 16, v76
	v_lshlrev_b32_e32 v149, 16, v77
	v_and_b32_e32 v150, 0xffff0000, v76
	v_and_b32_e32 v151, 0xffff0000, v77
	v_lshlrev_b32_e32 v152, 16, v78
	v_lshlrev_b32_e32 v153, 16, v79
	v_and_b32_e32 v154, 0xffff0000, v78
	v_and_b32_e32 v155, 0xffff0000, v79
	v_pk_mul_f32 v[150:151], v[150:151], v[150:151]
	v_pk_mul_f32 v[154:155], v[154:155], v[154:155]
	v_pk_fma_f32 v[148:149], v[148:149], v[148:149], v[150:151]
	v_pk_fma_f32 v[152:153], v[152:153], v[152:153], v[154:155]
	s_nop 0
	v_add_f32_e32 v148, v148, v149
	v_add_f32_e32 v152, v152, v153
	v_add_f32_e32 v158, v148, v152
	s_waitcnt vmcnt(9)
	v_permlane16_swap_b32_e32 v20, v16
	v_permlane16_swap_b32_e32 v21, v17
	v_permlane16_swap_b32_e32 v22, v18
	v_permlane16_swap_b32_e32 v23, v19
	v_mul_f32_e32 v20, 0xbfb8aa3b, v20
	v_mul_f32_e32 v21, 0xbfb8aa3b, v21
	v_mul_f32_e32 v22, 0xbfb8aa3b, v22
	v_mul_f32_e32 v23, 0xbfb8aa3b, v23
	v_mul_f32_e32 v16, 0xbfb8aa3b, v16
	v_mul_f32_e32 v17, 0xbfb8aa3b, v17
	v_mul_f32_e32 v18, 0xbfb8aa3b, v18
	v_mul_f32_e32 v19, 0xbfb8aa3b, v19
	v_exp_f32_e32 v20, v20
	v_exp_f32_e32 v21, v21
	v_exp_f32_e32 v22, v22
	v_exp_f32_e32 v23, v23
	v_exp_f32_e32 v16, v16
	v_exp_f32_e32 v17, v17
	v_exp_f32_e32 v18, v18
	v_exp_f32_e32 v19, v19
	v_add_f32_e32 v20, 1.0, v20
	v_add_f32_e32 v21, 1.0, v21
	v_add_f32_e32 v22, 1.0, v22
	v_add_f32_e32 v23, 1.0, v23
	v_add_f32_e32 v16, 1.0, v16
	v_add_f32_e32 v17, 1.0, v17
	v_add_f32_e32 v18, 1.0, v18
	v_add_f32_e32 v19, 1.0, v19
	v_rcp_f32_e32 v20, v20
	v_rcp_f32_e32 v21, v21
	v_rcp_f32_e32 v22, v22
	v_rcp_f32_e32 v23, v23
	v_rcp_f32_e32 v16, v16
	v_rcp_f32_e32 v17, v17
	v_rcp_f32_e32 v18, v18
	v_rcp_f32_e32 v19, v19
	v_lshlrev_b32_e32 v148, 16, v68
	v_lshlrev_b32_e32 v149, 16, v64
	v_and_b32_e32 v150, 0xffff0000, v68
	v_and_b32_e32 v151, 0xffff0000, v64
	v_fma_f32 v20, v20, v149, v148
	v_fma_f32 v21, v21, v151, v150
	v_lshlrev_b32_e32 v152, 16, v69
	v_lshlrev_b32_e32 v153, 16, v65
	v_and_b32_e32 v154, 0xffff0000, v69
	v_and_b32_e32 v155, 0xffff0000, v65
	v_fma_f32 v22, v22, v153, v152
	v_fma_f32 v23, v23, v155, v154
	v_lshlrev_b32_e32 v148, 16, v70
	v_lshlrev_b32_e32 v149, 16, v66
	v_and_b32_e32 v150, 0xffff0000, v70
	v_and_b32_e32 v151, 0xffff0000, v66
	v_fma_f32 v16, v16, v149, v148
	v_fma_f32 v17, v17, v151, v150
	v_lshlrev_b32_e32 v152, 16, v71
	v_lshlrev_b32_e32 v153, 16, v67
	v_and_b32_e32 v154, 0xffff0000, v71
	v_and_b32_e32 v155, 0xffff0000, v67
	v_fma_f32 v18, v18, v153, v152
	v_fma_f32 v19, v19, v155, v154
	v_cvt_pk_bf16_f32 v68, v20, v21
	v_cvt_pk_bf16_f32 v69, v22, v23
	v_cvt_pk_bf16_f32 v70, v16, v17
	v_cvt_pk_bf16_f32 v71, v18, v19
	s_add_u32 s28, s0, 0x50000
	s_addc_u32 s29, s1, 0
	global_store_dwordx4 v136, v[68:71], s[28:29] offset:256 nt
	v_lshlrev_b32_e32 v148, 16, v68
	v_lshlrev_b32_e32 v149, 16, v69
	v_and_b32_e32 v150, 0xffff0000, v68
	v_and_b32_e32 v151, 0xffff0000, v69
	v_lshlrev_b32_e32 v152, 16, v70
	v_lshlrev_b32_e32 v153, 16, v71
	v_and_b32_e32 v154, 0xffff0000, v70
	v_and_b32_e32 v155, 0xffff0000, v71
	v_pk_mul_f32 v[150:151], v[150:151], v[150:151]
	v_pk_mul_f32 v[154:155], v[154:155], v[154:155]
	v_pk_fma_f32 v[148:149], v[148:149], v[148:149], v[150:151]
	v_pk_fma_f32 v[152:153], v[152:153], v[152:153], v[154:155]
	s_nop 0
	v_add_f32_e32 v148, v148, v149
	v_add_f32_e32 v152, v152, v153
	v_add_f32_e32 v158, v158, v148
	v_add_f32_e32 v158, v158, v152
	s_waitcnt vmcnt(7)
	v_permlane16_swap_b32_e32 v12, v8
	v_permlane16_swap_b32_e32 v13, v9
	v_permlane16_swap_b32_e32 v14, v10
	v_permlane16_swap_b32_e32 v15, v11
	v_mul_f32_e32 v12, 0xbfb8aa3b, v12
	v_mul_f32_e32 v13, 0xbfb8aa3b, v13
	v_mul_f32_e32 v14, 0xbfb8aa3b, v14
	v_mul_f32_e32 v15, 0xbfb8aa3b, v15
	v_mul_f32_e32 v8, 0xbfb8aa3b, v8
	v_mul_f32_e32 v9, 0xbfb8aa3b, v9
	v_mul_f32_e32 v10, 0xbfb8aa3b, v10
	v_mul_f32_e32 v11, 0xbfb8aa3b, v11
	v_exp_f32_e32 v12, v12
	v_exp_f32_e32 v13, v13
	v_exp_f32_e32 v14, v14
	v_exp_f32_e32 v15, v15
	v_exp_f32_e32 v8, v8
	v_exp_f32_e32 v9, v9
	v_exp_f32_e32 v10, v10
	v_exp_f32_e32 v11, v11
	v_add_f32_e32 v12, 1.0, v12
	v_add_f32_e32 v13, 1.0, v13
	v_add_f32_e32 v14, 1.0, v14
	v_add_f32_e32 v15, 1.0, v15
	v_add_f32_e32 v8, 1.0, v8
	v_add_f32_e32 v9, 1.0, v9
	v_add_f32_e32 v10, 1.0, v10
	v_add_f32_e32 v11, 1.0, v11
	v_rcp_f32_e32 v12, v12
	v_rcp_f32_e32 v13, v13
	v_rcp_f32_e32 v14, v14
	v_rcp_f32_e32 v15, v15
	v_rcp_f32_e32 v8, v8
	v_rcp_f32_e32 v9, v9
	v_rcp_f32_e32 v10, v10
	v_rcp_f32_e32 v11, v11
	v_lshlrev_b32_e32 v148, 16, v60
	v_lshlrev_b32_e32 v149, 16, v56
	v_and_b32_e32 v150, 0xffff0000, v60
	v_and_b32_e32 v151, 0xffff0000, v56
	v_fma_f32 v12, v12, v149, v148
	v_fma_f32 v13, v13, v151, v150
	v_lshlrev_b32_e32 v152, 16, v61
	v_lshlrev_b32_e32 v153, 16, v57
	v_and_b32_e32 v154, 0xffff0000, v61
	v_and_b32_e32 v155, 0xffff0000, v57
	v_fma_f32 v14, v14, v153, v152
	v_fma_f32 v15, v15, v155, v154
	v_lshlrev_b32_e32 v148, 16, v62
	v_lshlrev_b32_e32 v149, 16, v58
	v_and_b32_e32 v150, 0xffff0000, v62
	v_and_b32_e32 v151, 0xffff0000, v58
	v_fma_f32 v8, v8, v149, v148
	v_fma_f32 v9, v9, v151, v150
	v_lshlrev_b32_e32 v152, 16, v63
	v_lshlrev_b32_e32 v153, 16, v59
	v_and_b32_e32 v154, 0xffff0000, v63
	v_and_b32_e32 v155, 0xffff0000, v59
	v_fma_f32 v10, v10, v153, v152
	v_fma_f32 v11, v11, v155, v154
	v_cvt_pk_bf16_f32 v60, v12, v13
	v_cvt_pk_bf16_f32 v61, v14, v15
	v_cvt_pk_bf16_f32 v62, v8, v9
	v_cvt_pk_bf16_f32 v63, v10, v11
	s_add_u32 s28, s0, 0x58000
	s_addc_u32 s29, s1, 0
	global_store_dwordx4 v136, v[60:63], s[28:29] nt
	v_lshlrev_b32_e32 v148, 16, v60
	v_lshlrev_b32_e32 v149, 16, v61
	v_and_b32_e32 v150, 0xffff0000, v60
	v_and_b32_e32 v151, 0xffff0000, v61
	v_lshlrev_b32_e32 v152, 16, v62
	v_lshlrev_b32_e32 v153, 16, v63
	v_and_b32_e32 v154, 0xffff0000, v62
	v_and_b32_e32 v155, 0xffff0000, v63
	v_pk_mul_f32 v[150:151], v[150:151], v[150:151]
	v_pk_mul_f32 v[154:155], v[154:155], v[154:155]
	v_pk_fma_f32 v[148:149], v[148:149], v[148:149], v[150:151]
	v_pk_fma_f32 v[152:153], v[152:153], v[152:153], v[154:155]
	s_nop 0
	v_add_f32_e32 v148, v148, v149
	v_add_f32_e32 v152, v152, v153
	v_add_f32_e32 v159, v148, v152
	s_waitcnt vmcnt(5)
	v_permlane16_swap_b32_e32 v4, v0
	v_permlane16_swap_b32_e32 v5, v1
	v_permlane16_swap_b32_e32 v6, v2
	v_permlane16_swap_b32_e32 v7, v3
	v_mul_f32_e32 v4, 0xbfb8aa3b, v4
	v_mul_f32_e32 v5, 0xbfb8aa3b, v5
	v_mul_f32_e32 v6, 0xbfb8aa3b, v6
	v_mul_f32_e32 v7, 0xbfb8aa3b, v7
	v_mul_f32_e32 v0, 0xbfb8aa3b, v0
	v_mul_f32_e32 v1, 0xbfb8aa3b, v1
	v_mul_f32_e32 v2, 0xbfb8aa3b, v2
	v_mul_f32_e32 v3, 0xbfb8aa3b, v3
	v_exp_f32_e32 v4, v4
	v_exp_f32_e32 v5, v5
	v_exp_f32_e32 v6, v6
	v_exp_f32_e32 v7, v7
	v_exp_f32_e32 v0, v0
	v_exp_f32_e32 v1, v1
	v_exp_f32_e32 v2, v2
	v_exp_f32_e32 v3, v3
	v_add_f32_e32 v4, 1.0, v4
	v_add_f32_e32 v5, 1.0, v5
	v_add_f32_e32 v6, 1.0, v6
	v_add_f32_e32 v7, 1.0, v7
	v_add_f32_e32 v0, 1.0, v0
	v_add_f32_e32 v1, 1.0, v1
	v_add_f32_e32 v2, 1.0, v2
	v_add_f32_e32 v3, 1.0, v3
	v_rcp_f32_e32 v4, v4
	v_rcp_f32_e32 v5, v5
	v_rcp_f32_e32 v6, v6
	v_rcp_f32_e32 v7, v7
	v_rcp_f32_e32 v0, v0
	v_rcp_f32_e32 v1, v1
	v_rcp_f32_e32 v2, v2
	v_rcp_f32_e32 v3, v3
	v_lshlrev_b32_e32 v148, 16, v52
	v_lshlrev_b32_e32 v149, 16, v48
	v_and_b32_e32 v150, 0xffff0000, v52
	v_and_b32_e32 v151, 0xffff0000, v48
	v_fma_f32 v4, v4, v149, v148
	v_fma_f32 v5, v5, v151, v150
	v_lshlrev_b32_e32 v152, 16, v53
	v_lshlrev_b32_e32 v153, 16, v49
	v_and_b32_e32 v154, 0xffff0000, v53
	v_and_b32_e32 v155, 0xffff0000, v49
	v_fma_f32 v6, v6, v153, v152
	v_fma_f32 v7, v7, v155, v154
	v_lshlrev_b32_e32 v148, 16, v54
	v_lshlrev_b32_e32 v149, 16, v50
	v_and_b32_e32 v150, 0xffff0000, v54
	v_and_b32_e32 v151, 0xffff0000, v50
	v_fma_f32 v0, v0, v149, v148
	v_fma_f32 v1, v1, v151, v150
	v_lshlrev_b32_e32 v152, 16, v55
	v_lshlrev_b32_e32 v153, 16, v51
	v_and_b32_e32 v154, 0xffff0000, v55
	v_and_b32_e32 v155, 0xffff0000, v51
	v_fma_f32 v2, v2, v153, v152
	v_fma_f32 v3, v3, v155, v154
	v_cvt_pk_bf16_f32 v52, v4, v5
	v_cvt_pk_bf16_f32 v53, v6, v7
	v_cvt_pk_bf16_f32 v54, v0, v1
	v_cvt_pk_bf16_f32 v55, v2, v3
	s_add_u32 s28, s0, 0x58000
	s_addc_u32 s29, s1, 0
	global_store_dwordx4 v136, v[52:55], s[28:29] offset:256 nt
	v_lshlrev_b32_e32 v148, 16, v52
	v_lshlrev_b32_e32 v149, 16, v53
	v_and_b32_e32 v150, 0xffff0000, v52
	v_and_b32_e32 v151, 0xffff0000, v53
	v_lshlrev_b32_e32 v152, 16, v54
	v_lshlrev_b32_e32 v153, 16, v55
	v_and_b32_e32 v154, 0xffff0000, v54
	v_and_b32_e32 v155, 0xffff0000, v55
	v_pk_mul_f32 v[150:151], v[150:151], v[150:151]
	v_pk_mul_f32 v[154:155], v[154:155], v[154:155]
	v_pk_fma_f32 v[148:149], v[148:149], v[148:149], v[150:151]
	v_pk_fma_f32 v[152:153], v[152:153], v[152:153], v[154:155]
	s_nop 0
	v_add_f32_e32 v148, v148, v149
	v_add_f32_e32 v152, v152, v153
	v_add_f32_e32 v159, v159, v148
	v_add_f32_e32 v159, v159, v152
	ds_bpermute_b32 v148, v137, v156
	ds_bpermute_b32 v149, v137, v157
	ds_bpermute_b32 v150, v137, v158
	ds_bpermute_b32 v151, v137, v159
	s_waitcnt lgkmcnt(0)
	v_add_f32_e32 v156, v156, v148
	v_add_f32_e32 v157, v157, v149
	v_add_f32_e32 v158, v158, v150
	v_add_f32_e32 v159, v159, v151
	ds_bpermute_b32 v148, v138, v156
	ds_bpermute_b32 v149, v138, v157
	ds_bpermute_b32 v150, v138, v158
	ds_bpermute_b32 v151, v138, v159
	s_waitcnt lgkmcnt(0)
	v_add_f32_e32 v156, v156, v148
	v_add_f32_e32 v157, v157, v149
	v_add_f32_e32 v158, v158, v150
	v_add_f32_e32 v159, v159, v151
	s_and_saveexec_b64 vcc, s[4:5]
	ds_write_b32 v146, v156 offset:2048
	ds_write_b32 v146, v157 offset:2304
	ds_write_b32 v146, v158 offset:2560
	ds_write_b32 v146, v159 offset:2816
	s_or_b64 exec, exec, vcc
	v_readlane_b32 s48, v251, 32
	v_readlane_b32 s49, v251, 33
	s_movk_i32 s50, 0x7fff
	s_waitcnt lgkmcnt(0)
	s_barrier
	s_and_saveexec_b64 s[0:1], s[6:7]
	s_cbranch_execz .LBB0_821
	v_add_u32_e32 v0, 0, v142
	v_add_u32_e32 v0, 0x20000, v0
	s_waitcnt lgkmcnt(0)
	ds_read_b128 v[0:3], v0
	s_ashr_i32 s11, s10, 31
	s_waitcnt lgkmcnt(0)
	v_mov_b32_e32 v4, v1
	v_mov_b32_e32 v5, v2
	v_mov_b32_e32 v1, v3
	v_pk_add_f32 v[0:1], v[4:5], v[0:1]
	s_nop 0
	v_add_f32_e32 v2, v0, v1
	v_add_u32_e32 v0, s2, v172
	v_ashrrev_i32_e32 v1, 31, v0
	v_lshl_add_u64 v[0:1], v[0:1], 4, s[14:15]
	v_lshl_add_u64 v[0:1], s[10:11], 2, v[0:1]
	global_store_dword v[0:1], v2, off

.LBB0_947:
	s_lshl_b32 s2, s19, 8
	s_mov_b64 s[12:13], s[26:27]
	v_readlane_b32 s0, v251, 20
	v_readlane_b32 s1, v251, 21
	v_and_b32_e32 v140, 0x60, v191
	v_and_b32_e32 v141, 16, v209
	v_and_b32_e32 v142, 32, v209
	v_lshrrev_b32_e32 v142, 2, v142
	v_or3_b32 v140, v140, v141, v142
	v_lshl_or_b32 v140, s18, 8, v140
	v_add_u32_e32 v141, s2, v173
	v_lshlrev_b32_e32 v142, 11, v141
	v_lshl_add_u32 v136, v140, 1, v142
	v_lshlrev_b32_e32 v142, 12, v141
	v_lshl_add_u32 v137, v140, 2, v142
	v_xor_b32_e32 v138, 16, v209
	v_xor_b32_e32 v139, 32, v209
	v_lshlrev_b32_e32 v138, 2, v138
	v_lshlrev_b32_e32 v139, 2, v139
	s_and_b64 vcc, exec, s[26:27]
	s_cbranch_vccnz .Lresid_fin
	s_add_u32 s10, s0, 0x0
	s_addc_u32 s11, s1, 0
	global_load_dwordx4 v[140:143], v136, s[10:11]
	global_load_dwordx4 v[144:147], v136, s[10:11] offset:256
	s_add_u32 s10, s0, 0x8000
	s_addc_u32 s11, s1, 0
	global_load_dwordx4 v[148:151], v136, s[10:11]
	global_load_dwordx4 v[152:155], v136, s[10:11] offset:256
	s_add_u32 s10, s0, 0x10000
	s_addc_u32 s11, s1, 0
	global_load_dwordx4 v[156:159], v136, s[10:11]
	global_load_dwordx4 v[160:163], v136, s[10:11] offset:256
	s_add_u32 s10, s0, 0x18000
	s_addc_u32 s11, s1, 0
	global_load_dwordx4 v[164:167], v136, s[10:11]
	global_load_dwordx4 v[174:177], v136, s[10:11] offset:256
	s_waitcnt vmcnt(7)
	v_permlane16_swap_b32_e32 v126, v122
	v_permlane16_swap_b32_e32 v127, v123
	v_permlane16_swap_b32_e32 v128, v124
	v_permlane16_swap_b32_e32 v129, v125
	v_lshlrev_b32_e32 v178, 16, v140
	v_and_b32_e32 v179, 0xffff0000, v140
	v_lshlrev_b32_e32 v180, 16, v141
	v_and_b32_e32 v181, 0xffff0000, v141
	v_lshlrev_b32_e32 v182, 16, v142
	v_and_b32_e32 v183, 0xffff0000, v142
	v_lshlrev_b32_e32 v184, 16, v143
	v_and_b32_e32 v185, 0xffff0000, v143
	v_pk_fma_f32 v[126:127], s[14:15], v[126:127], v[178:179]
	v_pk_fma_f32 v[128:129], s[14:15], v[128:129], v[180:181]
	v_pk_fma_f32 v[122:123], s[14:15], v[122:123], v[182:183]
	v_pk_fma_f32 v[124:125], s[14:15], v[124:125], v[184:185]
	s_add_u32 s10, s0, 0x0
	s_addc_u32 s11, s1, 0
	v_cvt_pk_bf16_f32 v140, v126, v127
	v_cvt_pk_bf16_f32 v141, v128, v129
	v_cvt_pk_bf16_f32 v142, v122, v123
	v_cvt_pk_bf16_f32 v143, v124, v125
	global_store_dwordx4 v136, v[140:143], s[10:11] nt
	s_add_u32 s10, s0, 0x40000
	s_addc_u32 s11, s1, 0
	global_load_dwordx4 v[126:129], v136, s[10:11]
	v_lshlrev_b32_e32 v178, 16, v140
	v_lshlrev_b32_e32 v179, 16, v141
	v_and_b32_e32 v180, 0xffff0000, v140
	v_and_b32_e32 v181, 0xffff0000, v141
	v_lshlrev_b32_e32 v182, 16, v142
	v_lshlrev_b32_e32 v183, 16, v143
	v_and_b32_e32 v184, 0xffff0000, v142
	v_and_b32_e32 v185, 0xffff0000, v143
	v_pk_mul_f32 v[180:181], v[180:181], v[180:181]
	v_pk_mul_f32 v[184:185], v[184:185], v[184:185]
	v_pk_fma_f32 v[178:179], v[178:179], v[178:179], v[180:181]
	v_pk_fma_f32 v[182:183], v[182:183], v[182:183], v[184:185]
	s_nop 0
	v_add_f32_e32 v178, v178, v179
	v_add_f32_e32 v182, v182, v183
	v_add_f32_e32 v186, v178, v182
	s_waitcnt vmcnt(8)
	v_permlane16_swap_b32_e32 v118, v114
	v_permlane16_swap_b32_e32 v119, v115
	v_permlane16_swap_b32_e32 v120, v116
	v_permlane16_swap_b32_e32 v121, v117
	v_lshlrev_b32_e32 v178, 16, v144
	v_and_b32_e32 v179, 0xffff0000, v144
	v_lshlrev_b32_e32 v180, 16, v145
	v_and_b32_e32 v181, 0xffff0000, v145
	v_lshlrev_b32_e32 v182, 16, v146
	v_and_b32_e32 v183, 0xffff0000, v146
	v_lshlrev_b32_e32 v184, 16, v147
	v_and_b32_e32 v185, 0xffff0000, v147
	v_pk_fma_f32 v[118:119], s[14:15], v[118:119], v[178:179]
	v_pk_fma_f32 v[120:121], s[14:15], v[120:121], v[180:181]
	v_pk_fma_f32 v[114:115], s[14:15], v[114:115], v[182:183]
	v_pk_fma_f32 v[116:117], s[14:15], v[116:117], v[184:185]
	s_add_u32 s10, s0, 0x0
	s_addc_u32 s11, s1, 0
	v_cvt_pk_bf16_f32 v144, v118, v119
	v_cvt_pk_bf16_f32 v145, v120, v121
	v_cvt_pk_bf16_f32 v146, v114, v115
	v_cvt_pk_bf16_f32 v147, v116, v117
	global_store_dwordx4 v136, v[144:147], s[10:11] offset:256 nt
	s_add_u32 s10, s0, 0x40000
	s_addc_u32 s11, s1, 0
	global_load_dwordx4 v[118:121], v136, s[10:11] offset:256
	v_lshlrev_b32_e32 v178, 16, v144
	v_lshlrev_b32_e32 v179, 16, v145
	v_and_b32_e32 v180, 0xffff0000, v144
	v_and_b32_e32 v181, 0xffff0000, v145
	v_lshlrev_b32_e32 v182, 16, v146
	v_lshlrev_b32_e32 v183, 16, v147
	v_and_b32_e32 v184, 0xffff0000, v146
	v_and_b32_e32 v185, 0xffff0000, v147
	v_pk_mul_f32 v[180:181], v[180:181], v[180:181]
	v_pk_mul_f32 v[184:185], v[184:185], v[184:185]
	v_pk_fma_f32 v[178:179], v[178:179], v[178:179], v[180:181]
	v_pk_fma_f32 v[182:183], v[182:183], v[182:183], v[184:185]
	s_nop 0
	v_add_f32_e32 v178, v178, v179
	v_add_f32_e32 v182, v182, v183
	v_add_f32_e32 v186, v186, v178
	v_add_f32_e32 v186, v186, v182
	s_waitcnt vmcnt(9)
	v_permlane16_swap_b32_e32 v110, v106
	v_permlane16_swap_b32_e32 v111, v107
	v_permlane16_swap_b32_e32 v112, v108
	v_permlane16_swap_b32_e32 v113, v109
	v_lshlrev_b32_e32 v178, 16, v148
	v_and_b32_e32 v179, 0xffff0000, v148
	v_lshlrev_b32_e32 v180, 16, v149
	v_and_b32_e32 v181, 0xffff0000, v149
	v_lshlrev_b32_e32 v182, 16, v150
	v_and_b32_e32 v183, 0xffff0000, v150
	v_lshlrev_b32_e32 v184, 16, v151
	v_and_b32_e32 v185, 0xffff0000, v151
	v_pk_fma_f32 v[110:111], s[14:15], v[110:111], v[178:179]
	v_pk_fma_f32 v[112:113], s[14:15], v[112:113], v[180:181]
	v_pk_fma_f32 v[106:107], s[14:15], v[106:107], v[182:183]
	v_pk_fma_f32 v[108:109], s[14:15], v[108:109], v[184:185]
	s_add_u32 s10, s0, 0x8000
	s_addc_u32 s11, s1, 0
	v_cvt_pk_bf16_f32 v148, v110, v111
	v_cvt_pk_bf16_f32 v149, v112, v113
	v_cvt_pk_bf16_f32 v150, v106, v107
	v_cvt_pk_bf16_f32 v151, v108, v109
	global_store_dwordx4 v136, v[148:151], s[10:11] nt
	s_add_u32 s10, s0, 0x48000
	s_addc_u32 s11, s1, 0
	global_load_dwordx4 v[110:113], v136, s[10:11]
	v_lshlrev_b32_e32 v178, 16, v148
	v_lshlrev_b32_e32 v179, 16, v149
	v_and_b32_e32 v180, 0xffff0000, v148
	v_and_b32_e32 v181, 0xffff0000, v149
	v_lshlrev_b32_e32 v182, 16, v150
	v_lshlrev_b32_e32 v183, 16, v151
	v_and_b32_e32 v184, 0xffff0000, v150
	v_and_b32_e32 v185, 0xffff0000, v151
	v_pk_mul_f32 v[180:181], v[180:181], v[180:181]
	v_pk_mul_f32 v[184:185], v[184:185], v[184:185]
	v_pk_fma_f32 v[178:179], v[178:179], v[178:179], v[180:181]
	v_pk_fma_f32 v[182:183], v[182:183], v[182:183], v[184:185]
	s_nop 0
	v_add_f32_e32 v178, v178, v179
	v_add_f32_e32 v182, v182, v183
	v_add_f32_e32 v187, v178, v182
	s_waitcnt vmcnt(10)
	v_permlane16_swap_b32_e32 v102, v98
	v_permlane16_swap_b32_e32 v103, v99
	v_permlane16_swap_b32_e32 v104, v100
	v_permlane16_swap_b32_e32 v105, v101
	v_lshlrev_b32_e32 v178, 16, v152
	v_and_b32_e32 v179, 0xffff0000, v152
	v_lshlrev_b32_e32 v180, 16, v153
	v_and_b32_e32 v181, 0xffff0000, v153
	v_lshlrev_b32_e32 v182, 16, v154
	v_and_b32_e32 v183, 0xffff0000, v154
	v_lshlrev_b32_e32 v184, 16, v155
	v_and_b32_e32 v185, 0xffff0000, v155
	v_pk_fma_f32 v[102:103], s[14:15], v[102:103], v[178:179]
	v_pk_fma_f32 v[104:105], s[14:15], v[104:105], v[180:181]
	v_pk_fma_f32 v[98:99], s[14:15], v[98:99], v[182:183]
	v_pk_fma_f32 v[100:101], s[14:15], v[100:101], v[184:185]
	s_add_u32 s10, s0, 0x8000
	s_addc_u32 s11, s1, 0
	v_cvt_pk_bf16_f32 v152, v102, v103
	v_cvt_pk_bf16_f32 v153, v104, v105
	v_cvt_pk_bf16_f32 v154, v98, v99
	v_cvt_pk_bf16_f32 v155, v100, v101
	global_store_dwordx4 v136, v[152:155], s[10:11] offset:256 nt
	s_add_u32 s10, s0, 0x48000
	s_addc_u32 s11, s1, 0
	global_load_dwordx4 v[102:105], v136, s[10:11] offset:256
	v_lshlrev_b32_e32 v178, 16, v152
	v_lshlrev_b32_e32 v179, 16, v153
	v_and_b32_e32 v180, 0xffff0000, v152
	v_and_b32_e32 v181, 0xffff0000, v153
	v_lshlrev_b32_e32 v182, 16, v154
	v_lshlrev_b32_e32 v183, 16, v155
	v_and_b32_e32 v184, 0xffff0000, v154
	v_and_b32_e32 v185, 0xffff0000, v155
	v_pk_mul_f32 v[180:181], v[180:181], v[180:181]
	v_pk_mul_f32 v[184:185], v[184:185], v[184:185]
	v_pk_fma_f32 v[178:179], v[178:179], v[178:179], v[180:181]
	v_pk_fma_f32 v[182:183], v[182:183], v[182:183], v[184:185]
	s_nop 0
	v_add_f32_e32 v178, v178, v179
	v_add_f32_e32 v182, v182, v183
	v_add_f32_e32 v187, v187, v178
	v_add_f32_e32 v187, v187, v182
	s_waitcnt vmcnt(11)
	v_permlane16_swap_b32_e32 v92, v88
	v_permlane16_swap_b32_e32 v93, v89
	v_permlane16_swap_b32_e32 v94, v90
	v_permlane16_swap_b32_e32 v95, v91
	v_lshlrev_b32_e32 v178, 16, v156
	v_and_b32_e32 v179, 0xffff0000, v156
	v_lshlrev_b32_e32 v180, 16, v157
	v_and_b32_e32 v181, 0xffff0000, v157
	v_lshlrev_b32_e32 v182, 16, v158
	v_and_b32_e32 v183, 0xffff0000, v158
	v_lshlrev_b32_e32 v184, 16, v159
	v_and_b32_e32 v185, 0xffff0000, v159
	v_pk_fma_f32 v[92:93], s[14:15], v[92:93], v[178:179]
	v_pk_fma_f32 v[94:95], s[14:15], v[94:95], v[180:181]
	v_pk_fma_f32 v[88:89], s[14:15], v[88:89], v[182:183]
	v_pk_fma_f32 v[90:91], s[14:15], v[90:91], v[184:185]
	s_add_u32 s10, s0, 0x10000
	s_addc_u32 s11, s1, 0
	v_cvt_pk_bf16_f32 v156, v92, v93
	v_cvt_pk_bf16_f32 v157, v94, v95
	v_cvt_pk_bf16_f32 v158, v88, v89
	v_cvt_pk_bf16_f32 v159, v90, v91
	global_store_dwordx4 v136, v[156:159], s[10:11] nt
	s_add_u32 s10, s0, 0x50000
	s_addc_u32 s11, s1, 0
	global_load_dwordx4 v[92:95], v136, s[10:11]
	v_lshlrev_b32_e32 v178, 16, v156
	v_lshlrev_b32_e32 v179, 16, v157
	v_and_b32_e32 v180, 0xffff0000, v156
	v_and_b32_e32 v181, 0xffff0000, v157
	v_lshlrev_b32_e32 v182, 16, v158
	v_lshlrev_b32_e32 v183, 16, v159
	v_and_b32_e32 v184, 0xffff0000, v158
	v_and_b32_e32 v185, 0xffff0000, v159
	v_pk_mul_f32 v[180:181], v[180:181], v[180:181]
	v_pk_mul_f32 v[184:185], v[184:185], v[184:185]
	v_pk_fma_f32 v[178:179], v[178:179], v[178:179], v[180:181]
	v_pk_fma_f32 v[182:183], v[182:183], v[182:183], v[184:185]
	s_nop 0
	v_add_f32_e32 v178, v178, v179
	v_add_f32_e32 v182, v182, v183
	v_add_f32_e32 v188, v178, v182
	s_waitcnt vmcnt(12)
	v_permlane16_swap_b32_e32 v84, v80
	v_permlane16_swap_b32_e32 v85, v81
	v_permlane16_swap_b32_e32 v86, v82
	v_permlane16_swap_b32_e32 v87, v83
	v_lshlrev_b32_e32 v178, 16, v160
	v_and_b32_e32 v179, 0xffff0000, v160
	v_lshlrev_b32_e32 v180, 16, v161
	v_and_b32_e32 v181, 0xffff0000, v161
	v_lshlrev_b32_e32 v182, 16, v162
	v_and_b32_e32 v183, 0xffff0000, v162
	v_lshlrev_b32_e32 v184, 16, v163
	v_and_b32_e32 v185, 0xffff0000, v163
	v_pk_fma_f32 v[84:85], s[14:15], v[84:85], v[178:179]
	v_pk_fma_f32 v[86:87], s[14:15], v[86:87], v[180:181]
	v_pk_fma_f32 v[80:81], s[14:15], v[80:81], v[182:183]
	v_pk_fma_f32 v[82:83], s[14:15], v[82:83], v[184:185]
	s_add_u32 s10, s0, 0x10000
	s_addc_u32 s11, s1, 0
	v_cvt_pk_bf16_f32 v160, v84, v85
	v_cvt_pk_bf16_f32 v161, v86, v87
	v_cvt_pk_bf16_f32 v162, v80, v81
	v_cvt_pk_bf16_f32 v163, v82, v83
	global_store_dwordx4 v136, v[160:163], s[10:11] offset:256 nt
	s_add_u32 s10, s0, 0x50000
	s_addc_u32 s11, s1, 0
	global_load_dwordx4 v[84:87], v136, s[10:11] offset:256
	v_lshlrev_b32_e32 v178, 16, v160
	v_lshlrev_b32_e32 v179, 16, v161
	v_and_b32_e32 v180, 0xffff0000, v160
	v_and_b32_e32 v181, 0xffff0000, v161
	v_lshlrev_b32_e32 v182, 16, v162
	v_lshlrev_b32_e32 v183, 16, v163
	v_and_b32_e32 v184, 0xffff0000, v162
	v_and_b32_e32 v185, 0xffff0000, v163
	v_pk_mul_f32 v[180:181], v[180:181], v[180:181]
	v_pk_mul_f32 v[184:185], v[184:185], v[184:185]
	v_pk_fma_f32 v[178:179], v[178:179], v[178:179], v[180:181]
	v_pk_fma_f32 v[182:183], v[182:183], v[182:183], v[184:185]
	s_nop 0
	v_add_f32_e32 v178, v178, v179
	v_add_f32_e32 v182, v182, v183
	v_add_f32_e32 v188, v188, v178
	v_add_f32_e32 v188, v188, v182
	s_waitcnt vmcnt(13)
	v_permlane16_swap_b32_e32 v76, v72
	v_permlane16_swap_b32_e32 v77, v73
	v_permlane16_swap_b32_e32 v78, v74
	v_permlane16_swap_b32_e32 v79, v75
	v_lshlrev_b32_e32 v178, 16, v164
	v_and_b32_e32 v179, 0xffff0000, v164
	v_lshlrev_b32_e32 v180, 16, v165
	v_and_b32_e32 v181, 0xffff0000, v165
	v_lshlrev_b32_e32 v182, 16, v166
	v_and_b32_e32 v183, 0xffff0000, v166
	v_lshlrev_b32_e32 v184, 16, v167
	v_and_b32_e32 v185, 0xffff0000, v167
	v_pk_fma_f32 v[76:77], s[14:15], v[76:77], v[178:179]
	v_pk_fma_f32 v[78:79], s[14:15], v[78:79], v[180:181]
	v_pk_fma_f32 v[72:73], s[14:15], v[72:73], v[182:183]
	v_pk_fma_f32 v[74:75], s[14:15], v[74:75], v[184:185]
	s_add_u32 s10, s0, 0x18000
	s_addc_u32 s11, s1, 0
	v_cvt_pk_bf16_f32 v164, v76, v77
	v_cvt_pk_bf16_f32 v165, v78, v79
	v_cvt_pk_bf16_f32 v166, v72, v73
	v_cvt_pk_bf16_f32 v167, v74, v75
	global_store_dwordx4 v136, v[164:167], s[10:11] nt
	s_add_u32 s10, s0, 0x58000
	s_addc_u32 s11, s1, 0
	global_load_dwordx4 v[76:79], v136, s[10:11]
	v_lshlrev_b32_e32 v178, 16, v164
	v_lshlrev_b32_e32 v179, 16, v165
	v_and_b32_e32 v180, 0xffff0000, v164
	v_and_b32_e32 v181, 0xffff0000, v165
	v_lshlrev_b32_e32 v182, 16, v166
	v_lshlrev_b32_e32 v183, 16, v167
	v_and_b32_e32 v184, 0xffff0000, v166
	v_and_b32_e32 v185, 0xffff0000, v167
	v_pk_mul_f32 v[180:181], v[180:181], v[180:181]
	v_pk_mul_f32 v[184:185], v[184:185], v[184:185]
	v_pk_fma_f32 v[178:179], v[178:179], v[178:179], v[180:181]
	v_pk_fma_f32 v[182:183], v[182:183], v[182:183], v[184:185]
	s_nop 0
	v_add_f32_e32 v178, v178, v179
	v_add_f32_e32 v182, v182, v183
	v_add_f32_e32 v189, v178, v182
	s_waitcnt vmcnt(14)
	v_permlane16_swap_b32_e32 v68, v64
	v_permlane16_swap_b32_e32 v69, v65
	v_permlane16_swap_b32_e32 v70, v66
	v_permlane16_swap_b32_e32 v71, v67
	v_lshlrev_b32_e32 v178, 16, v174
	v_and_b32_e32 v179, 0xffff0000, v174
	v_lshlrev_b32_e32 v180, 16, v175
	v_and_b32_e32 v181, 0xffff0000, v175
	v_lshlrev_b32_e32 v182, 16, v176
	v_and_b32_e32 v183, 0xffff0000, v176
	v_lshlrev_b32_e32 v184, 16, v177
	v_and_b32_e32 v185, 0xffff0000, v177
	v_pk_fma_f32 v[68:69], s[14:15], v[68:69], v[178:179]
	v_pk_fma_f32 v[70:71], s[14:15], v[70:71], v[180:181]
	v_pk_fma_f32 v[64:65], s[14:15], v[64:65], v[182:183]
	v_pk_fma_f32 v[66:67], s[14:15], v[66:67], v[184:185]
	s_add_u32 s10, s0, 0x18000
	s_addc_u32 s11, s1, 0
	v_cvt_pk_bf16_f32 v174, v68, v69
	v_cvt_pk_bf16_f32 v175, v70, v71
	v_cvt_pk_bf16_f32 v176, v64, v65
	v_cvt_pk_bf16_f32 v177, v66, v67
	global_store_dwordx4 v136, v[174:177], s[10:11] offset:256 nt
	s_add_u32 s10, s0, 0x58000
	s_addc_u32 s11, s1, 0
	global_load_dwordx4 v[68:71], v136, s[10:11] offset:256
	v_lshlrev_b32_e32 v178, 16, v174
	v_lshlrev_b32_e32 v179, 16, v175
	v_and_b32_e32 v180, 0xffff0000, v174
	v_and_b32_e32 v181, 0xffff0000, v175
	v_lshlrev_b32_e32 v182, 16, v176
	v_lshlrev_b32_e32 v183, 16, v177
	v_and_b32_e32 v184, 0xffff0000, v176
	v_and_b32_e32 v185, 0xffff0000, v177
	v_pk_mul_f32 v[180:181], v[180:181], v[180:181]
	v_pk_mul_f32 v[184:185], v[184:185], v[184:185]
	v_pk_fma_f32 v[178:179], v[178:179], v[178:179], v[180:181]
	v_pk_fma_f32 v[182:183], v[182:183], v[182:183], v[184:185]
	s_nop 0
	v_add_f32_e32 v178, v178, v179
	v_add_f32_e32 v182, v182, v183
	v_add_f32_e32 v189, v189, v178
	v_add_f32_e32 v189, v189, v182
	ds_bpermute_b32 v178, v138, v186
	ds_bpermute_b32 v179, v138, v187
	ds_bpermute_b32 v180, v138, v188
	ds_bpermute_b32 v181, v138, v189
	s_waitcnt lgkmcnt(0)
	v_add_f32_e32 v186, v186, v178
	v_add_f32_e32 v187, v187, v179
	v_add_f32_e32 v188, v188, v180
	v_add_f32_e32 v189, v189, v181
	ds_bpermute_b32 v178, v139, v186
	ds_bpermute_b32 v179, v139, v187
	ds_bpermute_b32 v180, v139, v188
	ds_bpermute_b32 v181, v139, v189
	s_waitcnt lgkmcnt(0)
	v_add_f32_e32 v186, v186, v178
	v_add_f32_e32 v187, v187, v179
	v_add_f32_e32 v188, v188, v180
	v_add_f32_e32 v189, v189, v181
	s_and_saveexec_b64 vcc, s[4:5]
	ds_write_b32 v192, v186
	ds_write_b32 v192, v187 offset:256
	ds_write_b32 v192, v188 offset:512
	ds_write_b32 v192, v189 offset:768
	s_or_b64 exec, exec, vcc
	s_waitcnt vmcnt(14)
	v_permlane16_swap_b32_e32 v60, v56
	v_permlane16_swap_b32_e32 v61, v57
	v_permlane16_swap_b32_e32 v62, v58
	v_permlane16_swap_b32_e32 v63, v59
	v_lshlrev_b32_e32 v178, 16, v126
	v_and_b32_e32 v179, 0xffff0000, v126
	v_lshlrev_b32_e32 v180, 16, v127
	v_and_b32_e32 v181, 0xffff0000, v127
	v_lshlrev_b32_e32 v182, 16, v128
	v_and_b32_e32 v183, 0xffff0000, v128
	v_lshlrev_b32_e32 v184, 16, v129
	v_and_b32_e32 v185, 0xffff0000, v129
	v_pk_fma_f32 v[60:61], s[14:15], v[60:61], v[178:179]
	v_pk_fma_f32 v[62:63], s[14:15], v[62:63], v[180:181]
	v_pk_fma_f32 v[56:57], s[14:15], v[56:57], v[182:183]
	v_pk_fma_f32 v[58:59], s[14:15], v[58:59], v[184:185]
	s_add_u32 s10, s0, 0x40000
	s_addc_u32 s11, s1, 0
	v_cvt_pk_bf16_f32 v126, v60, v61
	v_cvt_pk_bf16_f32 v127, v62, v63
	v_cvt_pk_bf16_f32 v128, v56, v57
	v_cvt_pk_bf16_f32 v129, v58, v59
	global_store_dwordx4 v136, v[126:129], s[10:11] nt
	v_lshlrev_b32_e32 v178, 16, v126
	v_lshlrev_b32_e32 v179, 16, v127
	v_and_b32_e32 v180, 0xffff0000, v126
	v_and_b32_e32 v181, 0xffff0000, v127
	v_lshlrev_b32_e32 v182, 16, v128
	v_lshlrev_b32_e32 v183, 16, v129
	v_and_b32_e32 v184, 0xffff0000, v128
	v_and_b32_e32 v185, 0xffff0000, v129
	v_pk_mul_f32 v[180:181], v[180:181], v[180:181]
	v_pk_mul_f32 v[184:185], v[184:185], v[184:185]
	v_pk_fma_f32 v[178:179], v[178:179], v[178:179], v[180:181]
	v_pk_fma_f32 v[182:183], v[182:183], v[182:183], v[184:185]
	s_nop 0
	v_add_f32_e32 v178, v178, v179
	v_add_f32_e32 v182, v182, v183
	v_add_f32_e32 v186, v178, v182
	s_waitcnt vmcnt(13)
	v_permlane16_swap_b32_e32 v52, v48
	v_permlane16_swap_b32_e32 v53, v49
	v_permlane16_swap_b32_e32 v54, v50
	v_permlane16_swap_b32_e32 v55, v51
	v_lshlrev_b32_e32 v178, 16, v118
	v_and_b32_e32 v179, 0xffff0000, v118
	v_lshlrev_b32_e32 v180, 16, v119
	v_and_b32_e32 v181, 0xffff0000, v119
	v_lshlrev_b32_e32 v182, 16, v120
	v_and_b32_e32 v183, 0xffff0000, v120
	v_lshlrev_b32_e32 v184, 16, v121
	v_and_b32_e32 v185, 0xffff0000, v121
	v_pk_fma_f32 v[52:53], s[14:15], v[52:53], v[178:179]
	v_pk_fma_f32 v[54:55], s[14:15], v[54:55], v[180:181]
	v_pk_fma_f32 v[48:49], s[14:15], v[48:49], v[182:183]
	v_pk_fma_f32 v[50:51], s[14:15], v[50:51], v[184:185]
	s_add_u32 s10, s0, 0x40000
	s_addc_u32 s11, s1, 0
	v_cvt_pk_bf16_f32 v118, v52, v53
	v_cvt_pk_bf16_f32 v119, v54, v55
	v_cvt_pk_bf16_f32 v120, v48, v49
	v_cvt_pk_bf16_f32 v121, v50, v51
	global_store_dwordx4 v136, v[118:121], s[10:11] offset:256 nt
	v_lshlrev_b32_e32 v178, 16, v118
	v_lshlrev_b32_e32 v179, 16, v119
	v_and_b32_e32 v180, 0xffff0000, v118
	v_and_b32_e32 v181, 0xffff0000, v119
	v_lshlrev_b32_e32 v182, 16, v120
	v_lshlrev_b32_e32 v183, 16, v121
	v_and_b32_e32 v184, 0xffff0000, v120
	v_and_b32_e32 v185, 0xffff0000, v121
	v_pk_mul_f32 v[180:181], v[180:181], v[180:181]
	v_pk_mul_f32 v[184:185], v[184:185], v[184:185]
	v_pk_fma_f32 v[178:179], v[178:179], v[178:179], v[180:181]
	v_pk_fma_f32 v[182:183], v[182:183], v[182:183], v[184:185]
	s_nop 0
	v_add_f32_e32 v178, v178, v179
	v_add_f32_e32 v182, v182, v183
	v_add_f32_e32 v186, v186, v178
	v_add_f32_e32 v186, v186, v182
	s_waitcnt vmcnt(12)
	v_permlane16_swap_b32_e32 v44, v40
	v_permlane16_swap_b32_e32 v45, v41
	v_permlane16_swap_b32_e32 v46, v42
	v_permlane16_swap_b32_e32 v47, v43
	v_lshlrev_b32_e32 v178, 16, v110
	v_and_b32_e32 v179, 0xffff0000, v110
	v_lshlrev_b32_e32 v180, 16, v111
	v_and_b32_e32 v181, 0xffff0000, v111
	v_lshlrev_b32_e32 v182, 16, v112
	v_and_b32_e32 v183, 0xffff0000, v112
	v_lshlrev_b32_e32 v184, 16, v113
	v_and_b32_e32 v185, 0xffff0000, v113
	v_pk_fma_f32 v[44:45], s[14:15], v[44:45], v[178:179]
	v_pk_fma_f32 v[46:47], s[14:15], v[46:47], v[180:181]
	v_pk_fma_f32 v[40:41], s[14:15], v[40:41], v[182:183]
	v_pk_fma_f32 v[42:43], s[14:15], v[42:43], v[184:185]
	s_add_u32 s10, s0, 0x48000
	s_addc_u32 s11, s1, 0
	v_cvt_pk_bf16_f32 v110, v44, v45
	v_cvt_pk_bf16_f32 v111, v46, v47
	v_cvt_pk_bf16_f32 v112, v40, v41
	v_cvt_pk_bf16_f32 v113, v42, v43
	global_store_dwordx4 v136, v[110:113], s[10:11] nt
	v_lshlrev_b32_e32 v178, 16, v110
	v_lshlrev_b32_e32 v179, 16, v111
	v_and_b32_e32 v180, 0xffff0000, v110
	v_and_b32_e32 v181, 0xffff0000, v111
	v_lshlrev_b32_e32 v182, 16, v112
	v_lshlrev_b32_e32 v183, 16, v113
	v_and_b32_e32 v184, 0xffff0000, v112
	v_and_b32_e32 v185, 0xffff0000, v113
	v_pk_mul_f32 v[180:181], v[180:181], v[180:181]
	v_pk_mul_f32 v[184:185], v[184:185], v[184:185]
	v_pk_fma_f32 v[178:179], v[178:179], v[178:179], v[180:181]
	v_pk_fma_f32 v[182:183], v[182:183], v[182:183], v[184:185]
	s_nop 0
	v_add_f32_e32 v178, v178, v179
	v_add_f32_e32 v182, v182, v183
	v_add_f32_e32 v187, v178, v182
	s_waitcnt vmcnt(11)
	v_permlane16_swap_b32_e32 v36, v32
	v_permlane16_swap_b32_e32 v37, v33
	v_permlane16_swap_b32_e32 v38, v34
	v_permlane16_swap_b32_e32 v39, v35
	v_lshlrev_b32_e32 v178, 16, v102
	v_and_b32_e32 v179, 0xffff0000, v102
	v_lshlrev_b32_e32 v180, 16, v103
	v_and_b32_e32 v181, 0xffff0000, v103
	v_lshlrev_b32_e32 v182, 16, v104
	v_and_b32_e32 v183, 0xffff0000, v104
	v_lshlrev_b32_e32 v184, 16, v105
	v_and_b32_e32 v185, 0xffff0000, v105
	v_pk_fma_f32 v[36:37], s[14:15], v[36:37], v[178:179]
	v_pk_fma_f32 v[38:39], s[14:15], v[38:39], v[180:181]
	v_pk_fma_f32 v[32:33], s[14:15], v[32:33], v[182:183]
	v_pk_fma_f32 v[34:35], s[14:15], v[34:35], v[184:185]
	s_add_u32 s10, s0, 0x48000
	s_addc_u32 s11, s1, 0
	v_cvt_pk_bf16_f32 v102, v36, v37
	v_cvt_pk_bf16_f32 v103, v38, v39
	v_cvt_pk_bf16_f32 v104, v32, v33
	v_cvt_pk_bf16_f32 v105, v34, v35
	global_store_dwordx4 v136, v[102:105], s[10:11] offset:256 nt
	v_lshlrev_b32_e32 v178, 16, v102
	v_lshlrev_b32_e32 v179, 16, v103
	v_and_b32_e32 v180, 0xffff0000, v102
	v_and_b32_e32 v181, 0xffff0000, v103
	v_lshlrev_b32_e32 v182, 16, v104
	v_lshlrev_b32_e32 v183, 16, v105
	v_and_b32_e32 v184, 0xffff0000, v104
	v_and_b32_e32 v185, 0xffff0000, v105
	v_pk_mul_f32 v[180:181], v[180:181], v[180:181]
	v_pk_mul_f32 v[184:185], v[184:185], v[184:185]
	v_pk_fma_f32 v[178:179], v[178:179], v[178:179], v[180:181]
	v_pk_fma_f32 v[182:183], v[182:183], v[182:183], v[184:185]
	s_nop 0
	v_add_f32_e32 v178, v178, v179
	v_add_f32_e32 v182, v182, v183
	v_add_f32_e32 v187, v187, v178
	v_add_f32_e32 v187, v187, v182
	s_waitcnt vmcnt(10)
	v_permlane16_swap_b32_e32 v28, v24
	v_permlane16_swap_b32_e32 v29, v25
	v_permlane16_swap_b32_e32 v30, v26
	v_permlane16_swap_b32_e32 v31, v27
	v_lshlrev_b32_e32 v178, 16, v92
	v_and_b32_e32 v179, 0xffff0000, v92
	v_lshlrev_b32_e32 v180, 16, v93
	v_and_b32_e32 v181, 0xffff0000, v93
	v_lshlrev_b32_e32 v182, 16, v94
	v_and_b32_e32 v183, 0xffff0000, v94
	v_lshlrev_b32_e32 v184, 16, v95
	v_and_b32_e32 v185, 0xffff0000, v95
	v_pk_fma_f32 v[28:29], s[14:15], v[28:29], v[178:179]
	v_pk_fma_f32 v[30:31], s[14:15], v[30:31], v[180:181]
	v_pk_fma_f32 v[24:25], s[14:15], v[24:25], v[182:183]
	v_pk_fma_f32 v[26:27], s[14:15], v[26:27], v[184:185]
	s_add_u32 s10, s0, 0x50000
	s_addc_u32 s11, s1, 0
	v_cvt_pk_bf16_f32 v92, v28, v29
	v_cvt_pk_bf16_f32 v93, v30, v31
	v_cvt_pk_bf16_f32 v94, v24, v25
	v_cvt_pk_bf16_f32 v95, v26, v27
	global_store_dwordx4 v136, v[92:95], s[10:11] nt
	v_lshlrev_b32_e32 v178, 16, v92
	v_lshlrev_b32_e32 v179, 16, v93
	v_and_b32_e32 v180, 0xffff0000, v92
	v_and_b32_e32 v181, 0xffff0000, v93
	v_lshlrev_b32_e32 v182, 16, v94
	v_lshlrev_b32_e32 v183, 16, v95
	v_and_b32_e32 v184, 0xffff0000, v94
	v_and_b32_e32 v185, 0xffff0000, v95
	v_pk_mul_f32 v[180:181], v[180:181], v[180:181]
	v_pk_mul_f32 v[184:185], v[184:185], v[184:185]
	v_pk_fma_f32 v[178:179], v[178:179], v[178:179], v[180:181]
	v_pk_fma_f32 v[182:183], v[182:183], v[182:183], v[184:185]
	s_nop 0
	v_add_f32_e32 v178, v178, v179
	v_add_f32_e32 v182, v182, v183
	v_add_f32_e32 v188, v178, v182
	s_waitcnt vmcnt(9)
	v_permlane16_swap_b32_e32 v20, v16
	v_permlane16_swap_b32_e32 v21, v17
	v_permlane16_swap_b32_e32 v22, v18
	v_permlane16_swap_b32_e32 v23, v19
	v_lshlrev_b32_e32 v178, 16, v84
	v_and_b32_e32 v179, 0xffff0000, v84
	v_lshlrev_b32_e32 v180, 16, v85
	v_and_b32_e32 v181, 0xffff0000, v85
	v_lshlrev_b32_e32 v182, 16, v86
	v_and_b32_e32 v183, 0xffff0000, v86
	v_lshlrev_b32_e32 v184, 16, v87
	v_and_b32_e32 v185, 0xffff0000, v87
	v_pk_fma_f32 v[20:21], s[14:15], v[20:21], v[178:179]
	v_pk_fma_f32 v[22:23], s[14:15], v[22:23], v[180:181]
	v_pk_fma_f32 v[16:17], s[14:15], v[16:17], v[182:183]
	v_pk_fma_f32 v[18:19], s[14:15], v[18:19], v[184:185]
	s_add_u32 s10, s0, 0x50000
	s_addc_u32 s11, s1, 0
	v_cvt_pk_bf16_f32 v84, v20, v21
	v_cvt_pk_bf16_f32 v85, v22, v23
	v_cvt_pk_bf16_f32 v86, v16, v17
	v_cvt_pk_bf16_f32 v87, v18, v19
	global_store_dwordx4 v136, v[84:87], s[10:11] offset:256 nt
	v_lshlrev_b32_e32 v178, 16, v84
	v_lshlrev_b32_e32 v179, 16, v85
	v_and_b32_e32 v180, 0xffff0000, v84
	v_and_b32_e32 v181, 0xffff0000, v85
	v_lshlrev_b32_e32 v182, 16, v86
	v_lshlrev_b32_e32 v183, 16, v87
	v_and_b32_e32 v184, 0xffff0000, v86
	v_and_b32_e32 v185, 0xffff0000, v87
	v_pk_mul_f32 v[180:181], v[180:181], v[180:181]
	v_pk_mul_f32 v[184:185], v[184:185], v[184:185]
	v_pk_fma_f32 v[178:179], v[178:179], v[178:179], v[180:181]
	v_pk_fma_f32 v[182:183], v[182:183], v[182:183], v[184:185]
	s_nop 0
	v_add_f32_e32 v178, v178, v179
	v_add_f32_e32 v182, v182, v183
	v_add_f32_e32 v188, v188, v178
	v_add_f32_e32 v188, v188, v182
	s_waitcnt vmcnt(8)
	v_permlane16_swap_b32_e32 v12, v8
	v_permlane16_swap_b32_e32 v13, v9
	v_permlane16_swap_b32_e32 v14, v10
	v_permlane16_swap_b32_e32 v15, v11
	v_lshlrev_b32_e32 v178, 16, v76
	v_and_b32_e32 v179, 0xffff0000, v76
	v_lshlrev_b32_e32 v180, 16, v77
	v_and_b32_e32 v181, 0xffff0000, v77
	v_lshlrev_b32_e32 v182, 16, v78
	v_and_b32_e32 v183, 0xffff0000, v78
	v_lshlrev_b32_e32 v184, 16, v79
	v_and_b32_e32 v185, 0xffff0000, v79
	v_pk_fma_f32 v[12:13], s[14:15], v[12:13], v[178:179]
	v_pk_fma_f32 v[14:15], s[14:15], v[14:15], v[180:181]
	v_pk_fma_f32 v[8:9], s[14:15], v[8:9], v[182:183]
	v_pk_fma_f32 v[10:11], s[14:15], v[10:11], v[184:185]
	s_add_u32 s10, s0, 0x58000
	s_addc_u32 s11, s1, 0
	v_cvt_pk_bf16_f32 v76, v12, v13
	v_cvt_pk_bf16_f32 v77, v14, v15
	v_cvt_pk_bf16_f32 v78, v8, v9
	v_cvt_pk_bf16_f32 v79, v10, v11
	global_store_dwordx4 v136, v[76:79], s[10:11] nt
	v_lshlrev_b32_e32 v178, 16, v76
	v_lshlrev_b32_e32 v179, 16, v77
	v_and_b32_e32 v180, 0xffff0000, v76
	v_and_b32_e32 v181, 0xffff0000, v77
	v_lshlrev_b32_e32 v182, 16, v78
	v_lshlrev_b32_e32 v183, 16, v79
	v_and_b32_e32 v184, 0xffff0000, v78
	v_and_b32_e32 v185, 0xffff0000, v79
	v_pk_mul_f32 v[180:181], v[180:181], v[180:181]
	v_pk_mul_f32 v[184:185], v[184:185], v[184:185]
	v_pk_fma_f32 v[178:179], v[178:179], v[178:179], v[180:181]
	v_pk_fma_f32 v[182:183], v[182:183], v[182:183], v[184:185]
	s_nop 0
	v_add_f32_e32 v178, v178, v179
	v_add_f32_e32 v182, v182, v183
	v_add_f32_e32 v189, v178, v182
	s_waitcnt vmcnt(7)
	v_permlane16_swap_b32_e32 v4, v0
	v_permlane16_swap_b32_e32 v5, v1
	v_permlane16_swap_b32_e32 v6, v2
	v_permlane16_swap_b32_e32 v7, v3
	v_lshlrev_b32_e32 v178, 16, v68
	v_and_b32_e32 v179, 0xffff0000, v68
	v_lshlrev_b32_e32 v180, 16, v69
	v_and_b32_e32 v181, 0xffff0000, v69
	v_lshlrev_b32_e32 v182, 16, v70
	v_and_b32_e32 v183, 0xffff0000, v70
	v_lshlrev_b32_e32 v184, 16, v71
	v_and_b32_e32 v185, 0xffff0000, v71
	v_pk_fma_f32 v[4:5], s[14:15], v[4:5], v[178:179]
	v_pk_fma_f32 v[6:7], s[14:15], v[6:7], v[180:181]
	v_pk_fma_f32 v[0:1], s[14:15], v[0:1], v[182:183]
	v_pk_fma_f32 v[2:3], s[14:15], v[2:3], v[184:185]
	s_add_u32 s10, s0, 0x58000
	s_addc_u32 s11, s1, 0
	v_cvt_pk_bf16_f32 v68, v4, v5
	v_cvt_pk_bf16_f32 v69, v6, v7
	v_cvt_pk_bf16_f32 v70, v0, v1
	v_cvt_pk_bf16_f32 v71, v2, v3
	global_store_dwordx4 v136, v[68:71], s[10:11] offset:256 nt
	v_lshlrev_b32_e32 v178, 16, v68
	v_lshlrev_b32_e32 v179, 16, v69
	v_and_b32_e32 v180, 0xffff0000, v68
	v_and_b32_e32 v181, 0xffff0000, v69
	v_lshlrev_b32_e32 v182, 16, v70
	v_lshlrev_b32_e32 v183, 16, v71
	v_and_b32_e32 v184, 0xffff0000, v70
	v_and_b32_e32 v185, 0xffff0000, v71
	v_pk_mul_f32 v[180:181], v[180:181], v[180:181]
	v_pk_mul_f32 v[184:185], v[184:185], v[184:185]
	v_pk_fma_f32 v[178:179], v[178:179], v[178:179], v[180:181]
	v_pk_fma_f32 v[182:183], v[182:183], v[182:183], v[184:185]
	s_nop 0
	v_add_f32_e32 v178, v178, v179
	v_add_f32_e32 v182, v182, v183
	v_add_f32_e32 v189, v189, v178
	v_add_f32_e32 v189, v189, v182
	ds_bpermute_b32 v178, v138, v186
	ds_bpermute_b32 v179, v138, v187
	ds_bpermute_b32 v180, v138, v188
	ds_bpermute_b32 v181, v138, v189
	s_waitcnt lgkmcnt(0)
	v_add_f32_e32 v186, v186, v178
	v_add_f32_e32 v187, v187, v179
	v_add_f32_e32 v188, v188, v180
	v_add_f32_e32 v189, v189, v181
	ds_bpermute_b32 v178, v139, v186
	ds_bpermute_b32 v179, v139, v187
	ds_bpermute_b32 v180, v139, v188
	ds_bpermute_b32 v181, v139, v189
	s_waitcnt lgkmcnt(0)
	v_add_f32_e32 v186, v186, v178
	v_add_f32_e32 v187, v187, v179
	v_add_f32_e32 v188, v188, v180
	v_add_f32_e32 v189, v189, v181
	s_and_saveexec_b64 vcc, s[4:5]
	ds_write_b32 v192, v186 offset:2048
	ds_write_b32 v192, v187 offset:2304
	ds_write_b32 v192, v188 offset:2560
	ds_write_b32 v192, v189 offset:2816
	s_or_b64 exec, exec, vcc
	s_branch .LBB0_1107
.Lresid_fin:
	s_add_u32 s10, s0, 0x0
	s_addc_u32 s11, s1, 0
	global_load_dwordx4 v[140:143], v136, s[10:11]
	global_load_dwordx4 v[144:147], v136, s[10:11] offset:256
	s_add_u32 s10, s0, 0x8000
	s_addc_u32 s11, s1, 0
	global_load_dwordx4 v[148:151], v136, s[10:11]
	global_load_dwordx4 v[152:155], v136, s[10:11] offset:256
	s_add_u32 s10, s0, 0x10000
	s_addc_u32 s11, s1, 0
	global_load_dwordx4 v[156:159], v136, s[10:11]
	global_load_dwordx4 v[160:163], v136, s[10:11] offset:256
	s_add_u32 s10, s0, 0x18000
	s_addc_u32 s11, s1, 0
	global_load_dwordx4 v[164:167], v136, s[10:11]
	global_load_dwordx4 v[174:177], v136, s[10:11] offset:256
	s_waitcnt vmcnt(7)
	v_permlane16_swap_b32_e32 v126, v122
	v_permlane16_swap_b32_e32 v127, v123
	v_permlane16_swap_b32_e32 v128, v124
	v_permlane16_swap_b32_e32 v129, v125
	v_lshlrev_b32_e32 v178, 16, v140
	v_and_b32_e32 v179, 0xffff0000, v140
	v_lshlrev_b32_e32 v180, 16, v141
	v_and_b32_e32 v181, 0xffff0000, v141
	v_lshlrev_b32_e32 v182, 16, v142
	v_and_b32_e32 v183, 0xffff0000, v142
	v_lshlrev_b32_e32 v184, 16, v143
	v_and_b32_e32 v185, 0xffff0000, v143
	v_pk_fma_f32 v[126:127], s[14:15], v[126:127], v[178:179]
	v_pk_fma_f32 v[128:129], s[14:15], v[128:129], v[180:181]
	v_pk_fma_f32 v[122:123], s[14:15], v[122:123], v[182:183]
	v_pk_fma_f32 v[124:125], s[14:15], v[124:125], v[184:185]
	s_add_u32 s10, s16, 0x0
	s_addc_u32 s11, s17, 0
	global_store_dwordx4 v137, v[126:129], s[10:11] offset:0 nt
	global_store_dwordx4 v137, v[122:125], s[10:11] offset:16 nt
	s_add_u32 s10, s0, 0x40000
	s_addc_u32 s11, s1, 0
	global_load_dwordx4 v[140:143], v136, s[10:11]
	s_waitcnt vmcnt(9)
	v_permlane16_swap_b32_e32 v118, v114
	v_permlane16_swap_b32_e32 v119, v115
	v_permlane16_swap_b32_e32 v120, v116
	v_permlane16_swap_b32_e32 v121, v117
	v_lshlrev_b32_e32 v178, 16, v144
	v_and_b32_e32 v179, 0xffff0000, v144
	v_lshlrev_b32_e32 v180, 16, v145
	v_and_b32_e32 v181, 0xffff0000, v145
	v_lshlrev_b32_e32 v182, 16, v146
	v_and_b32_e32 v183, 0xffff0000, v146
	v_lshlrev_b32_e32 v184, 16, v147
	v_and_b32_e32 v185, 0xffff0000, v147
	v_pk_fma_f32 v[118:119], s[14:15], v[118:119], v[178:179]
	v_pk_fma_f32 v[120:121], s[14:15], v[120:121], v[180:181]
	v_pk_fma_f32 v[114:115], s[14:15], v[114:115], v[182:183]
	v_pk_fma_f32 v[116:117], s[14:15], v[116:117], v[184:185]
	s_add_u32 s10, s16, 0x0
	s_addc_u32 s11, s17, 0
	global_store_dwordx4 v137, v[118:121], s[10:11] offset:512 nt
	global_store_dwordx4 v137, v[114:117], s[10:11] offset:528 nt
	s_add_u32 s10, s0, 0x40000
	s_addc_u32 s11, s1, 0
	global_load_dwordx4 v[144:147], v136, s[10:11] offset:256
	s_waitcnt vmcnt(11)
	v_permlane16_swap_b32_e32 v110, v106
	v_permlane16_swap_b32_e32 v111, v107
	v_permlane16_swap_b32_e32 v112, v108
	v_permlane16_swap_b32_e32 v113, v109
	v_lshlrev_b32_e32 v178, 16, v148
	v_and_b32_e32 v179, 0xffff0000, v148
	v_lshlrev_b32_e32 v180, 16, v149
	v_and_b32_e32 v181, 0xffff0000, v149
	v_lshlrev_b32_e32 v182, 16, v150
	v_and_b32_e32 v183, 0xffff0000, v150
	v_lshlrev_b32_e32 v184, 16, v151
	v_and_b32_e32 v185, 0xffff0000, v151
	v_pk_fma_f32 v[110:111], s[14:15], v[110:111], v[178:179]
	v_pk_fma_f32 v[112:113], s[14:15], v[112:113], v[180:181]
	v_pk_fma_f32 v[106:107], s[14:15], v[106:107], v[182:183]
	v_pk_fma_f32 v[108:109], s[14:15], v[108:109], v[184:185]
	s_add_u32 s10, s16, 0x10000
	s_addc_u32 s11, s17, 0
	global_store_dwordx4 v137, v[110:113], s[10:11] offset:0 nt
	global_store_dwordx4 v137, v[106:109], s[10:11] offset:16 nt
	s_add_u32 s10, s0, 0x48000
	s_addc_u32 s11, s1, 0
	global_load_dwordx4 v[148:151], v136, s[10:11]
	s_waitcnt vmcnt(13)
	v_permlane16_swap_b32_e32 v102, v98
	v_permlane16_swap_b32_e32 v103, v99
	v_permlane16_swap_b32_e32 v104, v100
	v_permlane16_swap_b32_e32 v105, v101
	v_lshlrev_b32_e32 v178, 16, v152
	v_and_b32_e32 v179, 0xffff0000, v152
	v_lshlrev_b32_e32 v180, 16, v153
	v_and_b32_e32 v181, 0xffff0000, v153
	v_lshlrev_b32_e32 v182, 16, v154
	v_and_b32_e32 v183, 0xffff0000, v154
	v_lshlrev_b32_e32 v184, 16, v155
	v_and_b32_e32 v185, 0xffff0000, v155
	v_pk_fma_f32 v[102:103], s[14:15], v[102:103], v[178:179]
	v_pk_fma_f32 v[104:105], s[14:15], v[104:105], v[180:181]
	v_pk_fma_f32 v[98:99], s[14:15], v[98:99], v[182:183]
	v_pk_fma_f32 v[100:101], s[14:15], v[100:101], v[184:185]
	s_add_u32 s10, s16, 0x10000
	s_addc_u32 s11, s17, 0
	global_store_dwordx4 v137, v[102:105], s[10:11] offset:512 nt
	global_store_dwordx4 v137, v[98:101], s[10:11] offset:528 nt
	s_add_u32 s10, s0, 0x48000
	s_addc_u32 s11, s1, 0
	global_load_dwordx4 v[152:155], v136, s[10:11] offset:256
	s_waitcnt vmcnt(15)
	v_permlane16_swap_b32_e32 v92, v88
	v_permlane16_swap_b32_e32 v93, v89
	v_permlane16_swap_b32_e32 v94, v90
	v_permlane16_swap_b32_e32 v95, v91
	v_lshlrev_b32_e32 v178, 16, v156
	v_and_b32_e32 v179, 0xffff0000, v156
	v_lshlrev_b32_e32 v180, 16, v157
	v_and_b32_e32 v181, 0xffff0000, v157
	v_lshlrev_b32_e32 v182, 16, v158
	v_and_b32_e32 v183, 0xffff0000, v158
	v_lshlrev_b32_e32 v184, 16, v159
	v_and_b32_e32 v185, 0xffff0000, v159
	v_pk_fma_f32 v[92:93], s[14:15], v[92:93], v[178:179]
	v_pk_fma_f32 v[94:95], s[14:15], v[94:95], v[180:181]
	v_pk_fma_f32 v[88:89], s[14:15], v[88:89], v[182:183]
	v_pk_fma_f32 v[90:91], s[14:15], v[90:91], v[184:185]
	s_add_u32 s10, s16, 0x20000
	s_addc_u32 s11, s17, 0
	global_store_dwordx4 v137, v[92:95], s[10:11] offset:0 nt
	global_store_dwordx4 v137, v[88:91], s[10:11] offset:16 nt
	s_add_u32 s10, s0, 0x50000
	s_addc_u32 s11, s1, 0
	global_load_dwordx4 v[156:159], v136, s[10:11]
	s_waitcnt vmcnt(17)
	v_permlane16_swap_b32_e32 v84, v80
	v_permlane16_swap_b32_e32 v85, v81
	v_permlane16_swap_b32_e32 v86, v82
	v_permlane16_swap_b32_e32 v87, v83
	v_lshlrev_b32_e32 v178, 16, v160
	v_and_b32_e32 v179, 0xffff0000, v160
	v_lshlrev_b32_e32 v180, 16, v161
	v_and_b32_e32 v181, 0xffff0000, v161
	v_lshlrev_b32_e32 v182, 16, v162
	v_and_b32_e32 v183, 0xffff0000, v162
	v_lshlrev_b32_e32 v184, 16, v163
	v_and_b32_e32 v185, 0xffff0000, v163
	v_pk_fma_f32 v[84:85], s[14:15], v[84:85], v[178:179]
	v_pk_fma_f32 v[86:87], s[14:15], v[86:87], v[180:181]
	v_pk_fma_f32 v[80:81], s[14:15], v[80:81], v[182:183]
	v_pk_fma_f32 v[82:83], s[14:15], v[82:83], v[184:185]
	s_add_u32 s10, s16, 0x20000
	s_addc_u32 s11, s17, 0
	global_store_dwordx4 v137, v[84:87], s[10:11] offset:512 nt
	global_store_dwordx4 v137, v[80:83], s[10:11] offset:528 nt
	s_add_u32 s10, s0, 0x50000
	s_addc_u32 s11, s1, 0
	global_load_dwordx4 v[160:163], v136, s[10:11] offset:256
	s_waitcnt vmcnt(19)
	v_permlane16_swap_b32_e32 v76, v72
	v_permlane16_swap_b32_e32 v77, v73
	v_permlane16_swap_b32_e32 v78, v74
	v_permlane16_swap_b32_e32 v79, v75
	v_lshlrev_b32_e32 v178, 16, v164
	v_and_b32_e32 v179, 0xffff0000, v164
	v_lshlrev_b32_e32 v180, 16, v165
	v_and_b32_e32 v181, 0xffff0000, v165
	v_lshlrev_b32_e32 v182, 16, v166
	v_and_b32_e32 v183, 0xffff0000, v166
	v_lshlrev_b32_e32 v184, 16, v167
	v_and_b32_e32 v185, 0xffff0000, v167
	v_pk_fma_f32 v[76:77], s[14:15], v[76:77], v[178:179]
	v_pk_fma_f32 v[78:79], s[14:15], v[78:79], v[180:181]
	v_pk_fma_f32 v[72:73], s[14:15], v[72:73], v[182:183]
	v_pk_fma_f32 v[74:75], s[14:15], v[74:75], v[184:185]
	s_add_u32 s10, s16, 0x30000
	s_addc_u32 s11, s17, 0
	global_store_dwordx4 v137, v[76:79], s[10:11] offset:0 nt
	global_store_dwordx4 v137, v[72:75], s[10:11] offset:16 nt
	s_add_u32 s10, s0, 0x58000
	s_addc_u32 s11, s1, 0
	global_load_dwordx4 v[164:167], v136, s[10:11]
	s_waitcnt vmcnt(21)
	v_permlane16_swap_b32_e32 v68, v64
	v_permlane16_swap_b32_e32 v69, v65
	v_permlane16_swap_b32_e32 v70, v66
	v_permlane16_swap_b32_e32 v71, v67
	v_lshlrev_b32_e32 v178, 16, v174
	v_and_b32_e32 v179, 0xffff0000, v174
	v_lshlrev_b32_e32 v180, 16, v175
	v_and_b32_e32 v181, 0xffff0000, v175
	v_lshlrev_b32_e32 v182, 16, v176
	v_and_b32_e32 v183, 0xffff0000, v176
	v_lshlrev_b32_e32 v184, 16, v177
	v_and_b32_e32 v185, 0xffff0000, v177
	v_pk_fma_f32 v[68:69], s[14:15], v[68:69], v[178:179]
	v_pk_fma_f32 v[70:71], s[14:15], v[70:71], v[180:181]
	v_pk_fma_f32 v[64:65], s[14:15], v[64:65], v[182:183]
	v_pk_fma_f32 v[66:67], s[14:15], v[66:67], v[184:185]
	s_add_u32 s10, s16, 0x30000
	s_addc_u32 s11, s17, 0
	global_store_dwordx4 v137, v[68:71], s[10:11] offset:512 nt
	global_store_dwordx4 v137, v[64:67], s[10:11] offset:528 nt
	s_add_u32 s10, s0, 0x58000
	s_addc_u32 s11, s1, 0
	global_load_dwordx4 v[174:177], v136, s[10:11] offset:256
	s_waitcnt vmcnt(21)
	v_permlane16_swap_b32_e32 v60, v56
	v_permlane16_swap_b32_e32 v61, v57
	v_permlane16_swap_b32_e32 v62, v58
	v_permlane16_swap_b32_e32 v63, v59
	v_lshlrev_b32_e32 v178, 16, v140
	v_and_b32_e32 v179, 0xffff0000, v140
	v_lshlrev_b32_e32 v180, 16, v141
	v_and_b32_e32 v181, 0xffff0000, v141
	v_lshlrev_b32_e32 v182, 16, v142
	v_and_b32_e32 v183, 0xffff0000, v142
	v_lshlrev_b32_e32 v184, 16, v143
	v_and_b32_e32 v185, 0xffff0000, v143
	v_pk_fma_f32 v[60:61], s[14:15], v[60:61], v[178:179]
	v_pk_fma_f32 v[62:63], s[14:15], v[62:63], v[180:181]
	v_pk_fma_f32 v[56:57], s[14:15], v[56:57], v[182:183]
	v_pk_fma_f32 v[58:59], s[14:15], v[58:59], v[184:185]
	s_add_u32 s10, s16, 0x80000
	s_addc_u32 s11, s17, 0
	global_store_dwordx4 v137, v[60:63], s[10:11] offset:0 nt
	global_store_dwordx4 v137, v[56:59], s[10:11] offset:16 nt
	s_waitcnt vmcnt(20)
	v_permlane16_swap_b32_e32 v52, v48
	v_permlane16_swap_b32_e32 v53, v49
	v_permlane16_swap_b32_e32 v54, v50
	v_permlane16_swap_b32_e32 v55, v51
	v_lshlrev_b32_e32 v178, 16, v144
	v_and_b32_e32 v179, 0xffff0000, v144
	v_lshlrev_b32_e32 v180, 16, v145
	v_and_b32_e32 v181, 0xffff0000, v145
	v_lshlrev_b32_e32 v182, 16, v146
	v_and_b32_e32 v183, 0xffff0000, v146
	v_lshlrev_b32_e32 v184, 16, v147
	v_and_b32_e32 v185, 0xffff0000, v147
	v_pk_fma_f32 v[52:53], s[14:15], v[52:53], v[178:179]
	v_pk_fma_f32 v[54:55], s[14:15], v[54:55], v[180:181]
	v_pk_fma_f32 v[48:49], s[14:15], v[48:49], v[182:183]
	v_pk_fma_f32 v[50:51], s[14:15], v[50:51], v[184:185]
	s_add_u32 s10, s16, 0x80000
	s_addc_u32 s11, s17, 0
	global_store_dwordx4 v137, v[52:55], s[10:11] offset:512 nt
	global_store_dwordx4 v137, v[48:51], s[10:11] offset:528 nt
	s_waitcnt vmcnt(19)
	v_permlane16_swap_b32_e32 v44, v40
	v_permlane16_swap_b32_e32 v45, v41
	v_permlane16_swap_b32_e32 v46, v42
	v_permlane16_swap_b32_e32 v47, v43
	v_lshlrev_b32_e32 v178, 16, v148
	v_and_b32_e32 v179, 0xffff0000, v148
	v_lshlrev_b32_e32 v180, 16, v149
	v_and_b32_e32 v181, 0xffff0000, v149
	v_lshlrev_b32_e32 v182, 16, v150
	v_and_b32_e32 v183, 0xffff0000, v150
	v_lshlrev_b32_e32 v184, 16, v151
	v_and_b32_e32 v185, 0xffff0000, v151
	v_pk_fma_f32 v[44:45], s[14:15], v[44:45], v[178:179]
	v_pk_fma_f32 v[46:47], s[14:15], v[46:47], v[180:181]
	v_pk_fma_f32 v[40:41], s[14:15], v[40:41], v[182:183]
	v_pk_fma_f32 v[42:43], s[14:15], v[42:43], v[184:185]
	s_add_u32 s10, s16, 0x90000
	s_addc_u32 s11, s17, 0
	global_store_dwordx4 v137, v[44:47], s[10:11] offset:0 nt
	global_store_dwordx4 v137, v[40:43], s[10:11] offset:16 nt
	s_waitcnt vmcnt(18)
	v_permlane16_swap_b32_e32 v36, v32
	v_permlane16_swap_b32_e32 v37, v33
	v_permlane16_swap_b32_e32 v38, v34
	v_permlane16_swap_b32_e32 v39, v35
	v_lshlrev_b32_e32 v178, 16, v152
	v_and_b32_e32 v179, 0xffff0000, v152
	v_lshlrev_b32_e32 v180, 16, v153
	v_and_b32_e32 v181, 0xffff0000, v153
	v_lshlrev_b32_e32 v182, 16, v154
	v_and_b32_e32 v183, 0xffff0000, v154
	v_lshlrev_b32_e32 v184, 16, v155
	v_and_b32_e32 v185, 0xffff0000, v155
	v_pk_fma_f32 v[36:37], s[14:15], v[36:37], v[178:179]
	v_pk_fma_f32 v[38:39], s[14:15], v[38:39], v[180:181]
	v_pk_fma_f32 v[32:33], s[14:15], v[32:33], v[182:183]
	v_pk_fma_f32 v[34:35], s[14:15], v[34:35], v[184:185]
	s_add_u32 s10, s16, 0x90000
	s_addc_u32 s11, s17, 0
	global_store_dwordx4 v137, v[36:39], s[10:11] offset:512 nt
	global_store_dwordx4 v137, v[32:35], s[10:11] offset:528 nt
	s_waitcnt vmcnt(17)
	v_permlane16_swap_b32_e32 v28, v24
	v_permlane16_swap_b32_e32 v29, v25
	v_permlane16_swap_b32_e32 v30, v26
	v_permlane16_swap_b32_e32 v31, v27
	v_lshlrev_b32_e32 v178, 16, v156
	v_and_b32_e32 v179, 0xffff0000, v156
	v_lshlrev_b32_e32 v180, 16, v157
	v_and_b32_e32 v181, 0xffff0000, v157
	v_lshlrev_b32_e32 v182, 16, v158
	v_and_b32_e32 v183, 0xffff0000, v158
	v_lshlrev_b32_e32 v184, 16, v159
	v_and_b32_e32 v185, 0xffff0000, v159
	v_pk_fma_f32 v[28:29], s[14:15], v[28:29], v[178:179]
	v_pk_fma_f32 v[30:31], s[14:15], v[30:31], v[180:181]
	v_pk_fma_f32 v[24:25], s[14:15], v[24:25], v[182:183]
	v_pk_fma_f32 v[26:27], s[14:15], v[26:27], v[184:185]
	s_add_u32 s10, s16, 0xa0000
	s_addc_u32 s11, s17, 0
	global_store_dwordx4 v137, v[28:31], s[10:11] offset:0 nt
	global_store_dwordx4 v137, v[24:27], s[10:11] offset:16 nt
	s_waitcnt vmcnt(16)
	v_permlane16_swap_b32_e32 v20, v16
	v_permlane16_swap_b32_e32 v21, v17
	v_permlane16_swap_b32_e32 v22, v18
	v_permlane16_swap_b32_e32 v23, v19
	v_lshlrev_b32_e32 v178, 16, v160
	v_and_b32_e32 v179, 0xffff0000, v160
	v_lshlrev_b32_e32 v180, 16, v161
	v_and_b32_e32 v181, 0xffff0000, v161
	v_lshlrev_b32_e32 v182, 16, v162
	v_and_b32_e32 v183, 0xffff0000, v162
	v_lshlrev_b32_e32 v184, 16, v163
	v_and_b32_e32 v185, 0xffff0000, v163
	v_pk_fma_f32 v[20:21], s[14:15], v[20:21], v[178:179]
	v_pk_fma_f32 v[22:23], s[14:15], v[22:23], v[180:181]
	v_pk_fma_f32 v[16:17], s[14:15], v[16:17], v[182:183]
	v_pk_fma_f32 v[18:19], s[14:15], v[18:19], v[184:185]
	s_add_u32 s10, s16, 0xa0000
	s_addc_u32 s11, s17, 0
	global_store_dwordx4 v137, v[20:23], s[10:11] offset:512 nt
	global_store_dwordx4 v137, v[16:19], s[10:11] offset:528 nt
	s_waitcnt vmcnt(15)
	v_permlane16_swap_b32_e32 v12, v8
	v_permlane16_swap_b32_e32 v13, v9
	v_permlane16_swap_b32_e32 v14, v10
	v_permlane16_swap_b32_e32 v15, v11
	v_lshlrev_b32_e32 v178, 16, v164
	v_and_b32_e32 v179, 0xffff0000, v164
	v_lshlrev_b32_e32 v180, 16, v165
	v_and_b32_e32 v181, 0xffff0000, v165
	v_lshlrev_b32_e32 v182, 16, v166
	v_and_b32_e32 v183, 0xffff0000, v166
	v_lshlrev_b32_e32 v184, 16, v167
	v_and_b32_e32 v185, 0xffff0000, v167
	v_pk_fma_f32 v[12:13], s[14:15], v[12:13], v[178:179]
	v_pk_fma_f32 v[14:15], s[14:15], v[14:15], v[180:181]
	v_pk_fma_f32 v[8:9], s[14:15], v[8:9], v[182:183]
	v_pk_fma_f32 v[10:11], s[14:15], v[10:11], v[184:185]
	s_add_u32 s10, s16, 0xb0000
	s_addc_u32 s11, s17, 0
	global_store_dwordx4 v137, v[12:15], s[10:11] offset:0 nt
	global_store_dwordx4 v137, v[8:11], s[10:11] offset:16 nt
	s_waitcnt vmcnt(14)
	v_permlane16_swap_b32_e32 v4, v0
	v_permlane16_swap_b32_e32 v5, v1
	v_permlane16_swap_b32_e32 v6, v2
	v_permlane16_swap_b32_e32 v7, v3
	v_lshlrev_b32_e32 v178, 16, v174
	v_and_b32_e32 v179, 0xffff0000, v174
	v_lshlrev_b32_e32 v180, 16, v175
	v_and_b32_e32 v181, 0xffff0000, v175
	v_lshlrev_b32_e32 v182, 16, v176
	v_and_b32_e32 v183, 0xffff0000, v176
	v_lshlrev_b32_e32 v184, 16, v177
	v_and_b32_e32 v185, 0xffff0000, v177
	v_pk_fma_f32 v[4:5], s[14:15], v[4:5], v[178:179]
	v_pk_fma_f32 v[6:7], s[14:15], v[6:7], v[180:181]
	v_pk_fma_f32 v[0:1], s[14:15], v[0:1], v[182:183]
	v_pk_fma_f32 v[2:3], s[14:15], v[2:3], v[184:185]
	s_add_u32 s10, s16, 0xb0000
	s_addc_u32 s11, s17, 0
	global_store_dwordx4 v137, v[4:7], s[10:11] offset:512 nt
	global_store_dwordx4 v137, v[0:3], s[10:11] offset:528 nt

.LBB0_1134:
	v_lshl_add_u32 v130, s0, 8, v148
	v_ashrrev_i32_e32 v131, 31, v130
	v_lshl_add_u64 v[190:191], v[130:131], 4, s[8:9]
	global_load_dwordx4 v[222:225], v[190:191], off
	global_load_dwordx4 v[226:229], v[190:191], off offset:256
	global_load_dwordx4 v[230:233], v[190:191], off offset:512
	global_load_dwordx4 v[234:237], v[190:191], off offset:768
	global_load_dwordx4 v[238:241], v[190:191], off offset:2048
	global_load_dwordx4 v[242:245], v[190:191], off offset:2304
	global_load_dwordx4 v[198:201], v[190:191], off offset:2560
	global_load_dwordx4 v[202:205], v[190:191], off offset:2816
	s_lshl_b32 s1, s1, 1
	s_or_b32 s1, s1, s36
	s_mul_hi_i32 s2, s0, 44
	s_mul_i32 s0, s0, 44
	s_ashr_i32 s3, s1, 31
	s_add_u32 s0, s0, s1
	s_addc_u32 s1, s2, s3
	s_lshl_b64 s[0:1], s[0:1], 15
	v_lshl_add_u64 v[178:179], v[166:167], 0, s[0:1]
	v_lshl_add_u64 v[178:179], v[178:179], 0, v[150:151]
	s_mov_b64 s[2:3], 0x1000
	v_lshl_add_u64 v[180:181], v[178:179], 0, s[2:3]
	s_mov_b64 s[2:3], 0x5000
	v_lshl_add_u64 v[182:183], v[178:179], 0, s[2:3]
	s_mov_b32 s2, 0xbfb8aa3b
	s_mov_b32 s3, 0xbfb8aa3b
	s_mov_b32 s100, 1.0
	s_mov_b32 s101, 1.0
	s_waitcnt vmcnt(7)
	v_add_f32_e32 v140, v222, v223
	v_add_f32_e32 v141, v224, v225
	v_add_f32_e32 v140, v140, v141
	v_fmamk_f32 v140, v140, 0x3a800000, v207
	v_rsq_f32_e32 v184, v140
	s_nop 0
	v_pk_mul_f32 v[118:119], v[118:119], v[184:185] op_sel_hi:[1,0]
	v_pk_mul_f32 v[120:121], v[120:121], v[184:185] op_sel_hi:[1,0]
	v_pk_mul_f32 v[114:115], v[114:115], v[184:185] op_sel_hi:[1,0]
	v_pk_mul_f32 v[116:117], v[116:117], v[184:185] op_sel_hi:[1,0]
	v_pk_mul_f32 v[126:127], v[126:127], v[184:185] op_sel_hi:[1,0]
	v_pk_mul_f32 v[128:129], v[128:129], v[184:185] op_sel_hi:[1,0]
	v_pk_mul_f32 v[122:123], v[122:123], v[184:185] op_sel_hi:[1,0]
	v_pk_mul_f32 v[124:125], v[124:125], v[184:185] op_sel_hi:[1,0]
	v_pk_mul_f32 v[132:133], v[118:119], s[2:3]
	v_pk_mul_f32 v[134:135], v[120:121], s[2:3]
	v_pk_mul_f32 v[136:137], v[114:115], s[2:3]
	v_pk_mul_f32 v[138:139], v[116:117], s[2:3]
	v_exp_f32_e32 v132, v132
	v_exp_f32_e32 v133, v133
	v_exp_f32_e32 v134, v134
	v_exp_f32_e32 v135, v135
	v_exp_f32_e32 v136, v136
	v_exp_f32_e32 v137, v137
	v_exp_f32_e32 v138, v138
	v_exp_f32_e32 v139, v139
	v_pk_add_f32 v[132:133], v[132:133], s[100:101]
	v_pk_add_f32 v[134:135], v[134:135], s[100:101]
	v_pk_add_f32 v[136:137], v[136:137], s[100:101]
	v_pk_add_f32 v[138:139], v[138:139], s[100:101]
	v_rcp_f32_e32 v132, v132
	v_rcp_f32_e32 v133, v133
	v_rcp_f32_e32 v134, v134
	v_rcp_f32_e32 v135, v135
	v_rcp_f32_e32 v136, v136
	v_rcp_f32_e32 v137, v137
	v_rcp_f32_e32 v138, v138
	v_rcp_f32_e32 v139, v139
	v_pk_mul_f32 v[118:119], v[118:119], v[132:133]
	v_pk_mul_f32 v[120:121], v[120:121], v[134:135]
	v_pk_mul_f32 v[114:115], v[114:115], v[136:137]
	v_pk_mul_f32 v[116:117], v[116:117], v[138:139]
	v_pk_mul_f32 v[118:119], v[118:119], v[126:127]
	v_pk_mul_f32 v[120:121], v[120:121], v[128:129]
	v_pk_mul_f32 v[114:115], v[114:115], v[122:123]
	v_pk_mul_f32 v[116:117], v[116:117], v[124:125]
	v_cvt_pk_bf16_f32 v192, v118, v119
	v_cvt_pk_bf16_f32 v193, v120, v121
	v_cvt_pk_bf16_f32 v194, v114, v115
	v_cvt_pk_bf16_f32 v195, v116, v117
	global_store_dwordx4 v[180:181], v[192:195], off offset:-4096 nt
	s_waitcnt vmcnt(7)
	v_add_f32_e32 v140, v226, v227
	v_add_f32_e32 v141, v228, v229
	v_add_f32_e32 v140, v140, v141
	v_fmamk_f32 v140, v140, 0x3a800000, v207
	v_rsq_f32_e32 v184, v140
	s_nop 0
	v_pk_mul_f32 v[110:111], v[110:111], v[184:185] op_sel_hi:[1,0]
	v_pk_mul_f32 v[112:113], v[112:113], v[184:185] op_sel_hi:[1,0]
	v_pk_mul_f32 v[102:103], v[102:103], v[184:185] op_sel_hi:[1,0]
	v_pk_mul_f32 v[104:105], v[104:105], v[184:185] op_sel_hi:[1,0]
	v_pk_mul_f32 v[106:107], v[106:107], v[184:185] op_sel_hi:[1,0]
	v_pk_mul_f32 v[108:109], v[108:109], v[184:185] op_sel_hi:[1,0]
	v_pk_mul_f32 v[98:99], v[98:99], v[184:185] op_sel_hi:[1,0]
	v_pk_mul_f32 v[100:101], v[100:101], v[184:185] op_sel_hi:[1,0]
	v_pk_mul_f32 v[132:133], v[110:111], s[2:3]
	v_pk_mul_f32 v[134:135], v[112:113], s[2:3]
	v_pk_mul_f32 v[136:137], v[102:103], s[2:3]
	v_pk_mul_f32 v[138:139], v[104:105], s[2:3]
	v_exp_f32_e32 v132, v132
	v_exp_f32_e32 v133, v133
	v_exp_f32_e32 v134, v134
	v_exp_f32_e32 v135, v135
	v_exp_f32_e32 v136, v136
	v_exp_f32_e32 v137, v137
	v_exp_f32_e32 v138, v138
	v_exp_f32_e32 v139, v139
	v_pk_add_f32 v[132:133], v[132:133], s[100:101]
	v_pk_add_f32 v[134:135], v[134:135], s[100:101]
	v_pk_add_f32 v[136:137], v[136:137], s[100:101]
	v_pk_add_f32 v[138:139], v[138:139], s[100:101]
	v_rcp_f32_e32 v132, v132
	v_rcp_f32_e32 v133, v133
	v_rcp_f32_e32 v134, v134
	v_rcp_f32_e32 v135, v135
	v_rcp_f32_e32 v136, v136
	v_rcp_f32_e32 v137, v137
	v_rcp_f32_e32 v138, v138
	v_rcp_f32_e32 v139, v139
	v_pk_mul_f32 v[110:111], v[110:111], v[132:133]
	v_pk_mul_f32 v[112:113], v[112:113], v[134:135]
	v_pk_mul_f32 v[102:103], v[102:103], v[136:137]
	v_pk_mul_f32 v[104:105], v[104:105], v[138:139]
	v_pk_mul_f32 v[110:111], v[110:111], v[106:107]
	v_pk_mul_f32 v[112:113], v[112:113], v[108:109]
	v_pk_mul_f32 v[102:103], v[102:103], v[98:99]
	v_pk_mul_f32 v[104:105], v[104:105], v[100:101]
	v_cvt_pk_bf16_f32 v186, v110, v111
	v_cvt_pk_bf16_f32 v187, v112, v113
	v_cvt_pk_bf16_f32 v188, v102, v103
	v_cvt_pk_bf16_f32 v189, v104, v105
	global_store_dwordx4 v[180:181], v[186:189], off offset:-2048 nt
	s_waitcnt vmcnt(7)
	v_add_f32_e32 v140, v230, v231
	v_add_f32_e32 v141, v232, v233
	v_add_f32_e32 v140, v140, v141
	v_fmamk_f32 v140, v140, 0x3a800000, v207
	v_rsq_f32_e32 v184, v140
	s_nop 0
	v_pk_mul_f32 v[92:93], v[92:93], v[184:185] op_sel_hi:[1,0]
	v_pk_mul_f32 v[94:95], v[94:95], v[184:185] op_sel_hi:[1,0]
	v_pk_mul_f32 v[84:85], v[84:85], v[184:185] op_sel_hi:[1,0]
	v_pk_mul_f32 v[86:87], v[86:87], v[184:185] op_sel_hi:[1,0]
	v_pk_mul_f32 v[88:89], v[88:89], v[184:185] op_sel_hi:[1,0]
	v_pk_mul_f32 v[90:91], v[90:91], v[184:185] op_sel_hi:[1,0]
	v_pk_mul_f32 v[80:81], v[80:81], v[184:185] op_sel_hi:[1,0]
	v_pk_mul_f32 v[82:83], v[82:83], v[184:185] op_sel_hi:[1,0]
	v_pk_mul_f32 v[132:133], v[92:93], s[2:3]
	v_pk_mul_f32 v[134:135], v[94:95], s[2:3]
	v_pk_mul_f32 v[136:137], v[84:85], s[2:3]
	v_pk_mul_f32 v[138:139], v[86:87], s[2:3]
	v_exp_f32_e32 v132, v132
	v_exp_f32_e32 v133, v133
	v_exp_f32_e32 v134, v134
	v_exp_f32_e32 v135, v135
	v_exp_f32_e32 v136, v136
	v_exp_f32_e32 v137, v137
	v_exp_f32_e32 v138, v138
	v_exp_f32_e32 v139, v139
	v_pk_add_f32 v[132:133], v[132:133], s[100:101]
	v_pk_add_f32 v[134:135], v[134:135], s[100:101]
	v_pk_add_f32 v[136:137], v[136:137], s[100:101]
	v_pk_add_f32 v[138:139], v[138:139], s[100:101]
	v_rcp_f32_e32 v132, v132
	v_rcp_f32_e32 v133, v133
	v_rcp_f32_e32 v134, v134
	v_rcp_f32_e32 v135, v135
	v_rcp_f32_e32 v136, v136
	v_rcp_f32_e32 v137, v137
	v_rcp_f32_e32 v138, v138
	v_rcp_f32_e32 v139, v139
	v_pk_mul_f32 v[92:93], v[92:93], v[132:133]
	v_pk_mul_f32 v[94:95], v[94:95], v[134:135]
	v_pk_mul_f32 v[84:85], v[84:85], v[136:137]
	v_pk_mul_f32 v[86:87], v[86:87], v[138:139]
	v_pk_mul_f32 v[92:93], v[92:93], v[88:89]
	v_pk_mul_f32 v[94:95], v[94:95], v[90:91]
	v_pk_mul_f32 v[84:85], v[84:85], v[80:81]
	v_pk_mul_f32 v[86:87], v[86:87], v[82:83]
	v_cvt_pk_bf16_f32 v192, v92, v93
	v_cvt_pk_bf16_f32 v193, v94, v95
	v_cvt_pk_bf16_f32 v194, v84, v85
	v_cvt_pk_bf16_f32 v195, v86, v87
	global_store_dwordx4 v[180:181], v[192:195], off nt
	s_waitcnt vmcnt(7)
	v_add_f32_e32 v140, v234, v235
	v_add_f32_e32 v141, v236, v237
	v_add_f32_e32 v140, v140, v141
	v_fmamk_f32 v140, v140, 0x3a800000, v207
	v_rsq_f32_e32 v184, v140
	s_nop 0
	v_pk_mul_f32 v[76:77], v[76:77], v[184:185] op_sel_hi:[1,0]
	v_pk_mul_f32 v[78:79], v[78:79], v[184:185] op_sel_hi:[1,0]
	v_pk_mul_f32 v[68:69], v[68:69], v[184:185] op_sel_hi:[1,0]
	v_pk_mul_f32 v[70:71], v[70:71], v[184:185] op_sel_hi:[1,0]
	v_pk_mul_f32 v[72:73], v[72:73], v[184:185] op_sel_hi:[1,0]
	v_pk_mul_f32 v[74:75], v[74:75], v[184:185] op_sel_hi:[1,0]
	v_pk_mul_f32 v[64:65], v[64:65], v[184:185] op_sel_hi:[1,0]
	v_pk_mul_f32 v[66:67], v[66:67], v[184:185] op_sel_hi:[1,0]
	v_pk_mul_f32 v[132:133], v[76:77], s[2:3]
	v_pk_mul_f32 v[134:135], v[78:79], s[2:3]
	v_pk_mul_f32 v[136:137], v[68:69], s[2:3]
	v_pk_mul_f32 v[138:139], v[70:71], s[2:3]
	v_exp_f32_e32 v132, v132
	v_exp_f32_e32 v133, v133
	v_exp_f32_e32 v134, v134
	v_exp_f32_e32 v135, v135
	v_exp_f32_e32 v136, v136
	v_exp_f32_e32 v137, v137
	v_exp_f32_e32 v138, v138
	v_exp_f32_e32 v139, v139
	v_pk_add_f32 v[132:133], v[132:133], s[100:101]
	v_pk_add_f32 v[134:135], v[134:135], s[100:101]
	v_pk_add_f32 v[136:137], v[136:137], s[100:101]
	v_pk_add_f32 v[138:139], v[138:139], s[100:101]
	v_rcp_f32_e32 v132, v132
	v_rcp_f32_e32 v133, v133
	v_rcp_f32_e32 v134, v134
	v_rcp_f32_e32 v135, v135
	v_rcp_f32_e32 v136, v136
	v_rcp_f32_e32 v137, v137
	v_rcp_f32_e32 v138, v138
	v_rcp_f32_e32 v139, v139
	v_pk_mul_f32 v[76:77], v[76:77], v[132:133]
	v_pk_mul_f32 v[78:79], v[78:79], v[134:135]
	v_pk_mul_f32 v[68:69], v[68:69], v[136:137]
	v_pk_mul_f32 v[70:71], v[70:71], v[138:139]
	v_pk_mul_f32 v[76:77], v[76:77], v[72:73]
	v_pk_mul_f32 v[78:79], v[78:79], v[74:75]
	v_pk_mul_f32 v[68:69], v[68:69], v[64:65]
	v_pk_mul_f32 v[70:71], v[70:71], v[66:67]
	v_cvt_pk_bf16_f32 v186, v76, v77
	v_cvt_pk_bf16_f32 v187, v78, v79
	v_cvt_pk_bf16_f32 v188, v68, v69
	v_cvt_pk_bf16_f32 v189, v70, v71
	global_store_dwordx4 v[180:181], v[186:189], off offset:2048 nt
	s_waitcnt vmcnt(7)
	v_add_f32_e32 v140, v238, v239
	v_add_f32_e32 v141, v240, v241
	v_add_f32_e32 v140, v140, v141
	v_fmamk_f32 v140, v140, 0x3a800000, v207
	v_rsq_f32_e32 v184, v140
	s_nop 0
	v_pk_mul_f32 v[60:61], v[60:61], v[184:185] op_sel_hi:[1,0]
	v_pk_mul_f32 v[62:63], v[62:63], v[184:185] op_sel_hi:[1,0]
	v_pk_mul_f32 v[52:53], v[52:53], v[184:185] op_sel_hi:[1,0]
	v_pk_mul_f32 v[54:55], v[54:55], v[184:185] op_sel_hi:[1,0]
	v_pk_mul_f32 v[56:57], v[56:57], v[184:185] op_sel_hi:[1,0]
	v_pk_mul_f32 v[58:59], v[58:59], v[184:185] op_sel_hi:[1,0]
	v_pk_mul_f32 v[48:49], v[48:49], v[184:185] op_sel_hi:[1,0]
	v_pk_mul_f32 v[50:51], v[50:51], v[184:185] op_sel_hi:[1,0]
	v_pk_mul_f32 v[132:133], v[60:61], s[2:3]
	v_pk_mul_f32 v[134:135], v[62:63], s[2:3]
	v_pk_mul_f32 v[136:137], v[52:53], s[2:3]
	v_pk_mul_f32 v[138:139], v[54:55], s[2:3]
	v_exp_f32_e32 v132, v132
	v_exp_f32_e32 v133, v133
	v_exp_f32_e32 v134, v134
	v_exp_f32_e32 v135, v135
	v_exp_f32_e32 v136, v136
	v_exp_f32_e32 v137, v137
	v_exp_f32_e32 v138, v138
	v_exp_f32_e32 v139, v139
	v_pk_add_f32 v[132:133], v[132:133], s[100:101]
	v_pk_add_f32 v[134:135], v[134:135], s[100:101]
	v_pk_add_f32 v[136:137], v[136:137], s[100:101]
	v_pk_add_f32 v[138:139], v[138:139], s[100:101]
	v_rcp_f32_e32 v132, v132
	v_rcp_f32_e32 v133, v133
	v_rcp_f32_e32 v134, v134
	v_rcp_f32_e32 v135, v135
	v_rcp_f32_e32 v136, v136
	v_rcp_f32_e32 v137, v137
	v_rcp_f32_e32 v138, v138
	v_rcp_f32_e32 v139, v139
	v_pk_mul_f32 v[60:61], v[60:61], v[132:133]
	v_pk_mul_f32 v[62:63], v[62:63], v[134:135]
	v_pk_mul_f32 v[52:53], v[52:53], v[136:137]
	v_pk_mul_f32 v[54:55], v[54:55], v[138:139]
	v_pk_mul_f32 v[60:61], v[60:61], v[56:57]
	v_pk_mul_f32 v[62:63], v[62:63], v[58:59]
	v_pk_mul_f32 v[52:53], v[52:53], v[48:49]
	v_pk_mul_f32 v[54:55], v[54:55], v[50:51]
	v_cvt_pk_bf16_f32 v192, v60, v61
	v_cvt_pk_bf16_f32 v193, v62, v63
	v_cvt_pk_bf16_f32 v194, v52, v53
	v_cvt_pk_bf16_f32 v195, v54, v55
	global_store_dwordx4 v[182:183], v[192:195], off offset:-4096 nt
	s_waitcnt vmcnt(7)
	v_add_f32_e32 v140, v242, v243
	v_add_f32_e32 v141, v244, v245
	v_add_f32_e32 v140, v140, v141
	v_fmamk_f32 v140, v140, 0x3a800000, v207
	v_rsq_f32_e32 v184, v140
	s_nop 0
	v_pk_mul_f32 v[44:45], v[44:45], v[184:185] op_sel_hi:[1,0]
	v_pk_mul_f32 v[46:47], v[46:47], v[184:185] op_sel_hi:[1,0]
	v_pk_mul_f32 v[36:37], v[36:37], v[184:185] op_sel_hi:[1,0]
	v_pk_mul_f32 v[38:39], v[38:39], v[184:185] op_sel_hi:[1,0]
	v_pk_mul_f32 v[40:41], v[40:41], v[184:185] op_sel_hi:[1,0]
	v_pk_mul_f32 v[42:43], v[42:43], v[184:185] op_sel_hi:[1,0]
	v_pk_mul_f32 v[32:33], v[32:33], v[184:185] op_sel_hi:[1,0]
	v_pk_mul_f32 v[34:35], v[34:35], v[184:185] op_sel_hi:[1,0]
	v_pk_mul_f32 v[132:133], v[44:45], s[2:3]
	v_pk_mul_f32 v[134:135], v[46:47], s[2:3]
	v_pk_mul_f32 v[136:137], v[36:37], s[2:3]
	v_pk_mul_f32 v[138:139], v[38:39], s[2:3]
	v_exp_f32_e32 v132, v132
	v_exp_f32_e32 v133, v133
	v_exp_f32_e32 v134, v134
	v_exp_f32_e32 v135, v135
	v_exp_f32_e32 v136, v136
	v_exp_f32_e32 v137, v137
	v_exp_f32_e32 v138, v138
	v_exp_f32_e32 v139, v139
	v_pk_add_f32 v[132:133], v[132:133], s[100:101]
	v_pk_add_f32 v[134:135], v[134:135], s[100:101]
	v_pk_add_f32 v[136:137], v[136:137], s[100:101]
	v_pk_add_f32 v[138:139], v[138:139], s[100:101]
	v_rcp_f32_e32 v132, v132
	v_rcp_f32_e32 v133, v133
	v_rcp_f32_e32 v134, v134
	v_rcp_f32_e32 v135, v135
	v_rcp_f32_e32 v136, v136
	v_rcp_f32_e32 v137, v137
	v_rcp_f32_e32 v138, v138
	v_rcp_f32_e32 v139, v139
	v_pk_mul_f32 v[44:45], v[44:45], v[132:133]
	v_pk_mul_f32 v[46:47], v[46:47], v[134:135]
	v_pk_mul_f32 v[36:37], v[36:37], v[136:137]
	v_pk_mul_f32 v[38:39], v[38:39], v[138:139]
	v_pk_mul_f32 v[44:45], v[44:45], v[40:41]
	v_pk_mul_f32 v[46:47], v[46:47], v[42:43]
	v_pk_mul_f32 v[36:37], v[36:37], v[32:33]
	v_pk_mul_f32 v[38:39], v[38:39], v[34:35]
	v_cvt_pk_bf16_f32 v186, v44, v45
	v_cvt_pk_bf16_f32 v187, v46, v47
	v_cvt_pk_bf16_f32 v188, v36, v37
	v_cvt_pk_bf16_f32 v189, v38, v39
	global_store_dwordx4 v[182:183], v[186:189], off offset:-2048 nt
	s_waitcnt vmcnt(7)
	v_add_f32_e32 v140, v198, v199
	v_add_f32_e32 v141, v200, v201
	v_add_f32_e32 v140, v140, v141
	v_fmamk_f32 v140, v140, 0x3a800000, v207
	v_rsq_f32_e32 v184, v140
	s_nop 0
	v_pk_mul_f32 v[28:29], v[28:29], v[184:185] op_sel_hi:[1,0]
	v_pk_mul_f32 v[30:31], v[30:31], v[184:185] op_sel_hi:[1,0]
	v_pk_mul_f32 v[20:21], v[20:21], v[184:185] op_sel_hi:[1,0]
	v_pk_mul_f32 v[22:23], v[22:23], v[184:185] op_sel_hi:[1,0]
	v_pk_mul_f32 v[24:25], v[24:25], v[184:185] op_sel_hi:[1,0]
	v_pk_mul_f32 v[26:27], v[26:27], v[184:185] op_sel_hi:[1,0]
	v_pk_mul_f32 v[16:17], v[16:17], v[184:185] op_sel_hi:[1,0]
	v_pk_mul_f32 v[18:19], v[18:19], v[184:185] op_sel_hi:[1,0]
	v_pk_mul_f32 v[132:133], v[28:29], s[2:3]
	v_pk_mul_f32 v[134:135], v[30:31], s[2:3]
	v_pk_mul_f32 v[136:137], v[20:21], s[2:3]
	v_pk_mul_f32 v[138:139], v[22:23], s[2:3]
	v_exp_f32_e32 v132, v132
	v_exp_f32_e32 v133, v133
	v_exp_f32_e32 v134, v134
	v_exp_f32_e32 v135, v135
	v_exp_f32_e32 v136, v136
	v_exp_f32_e32 v137, v137
	v_exp_f32_e32 v138, v138
	v_exp_f32_e32 v139, v139
	v_pk_add_f32 v[132:133], v[132:133], s[100:101]
	v_pk_add_f32 v[134:135], v[134:135], s[100:101]
	v_pk_add_f32 v[136:137], v[136:137], s[100:101]
	v_pk_add_f32 v[138:139], v[138:139], s[100:101]
	v_rcp_f32_e32 v132, v132
	v_rcp_f32_e32 v133, v133
	v_rcp_f32_e32 v134, v134
	v_rcp_f32_e32 v135, v135
	v_rcp_f32_e32 v136, v136
	v_rcp_f32_e32 v137, v137
	v_rcp_f32_e32 v138, v138
	v_rcp_f32_e32 v139, v139
	v_pk_mul_f32 v[28:29], v[28:29], v[132:133]
	v_pk_mul_f32 v[30:31], v[30:31], v[134:135]
	v_pk_mul_f32 v[20:21], v[20:21], v[136:137]
	v_pk_mul_f32 v[22:23], v[22:23], v[138:139]
	v_pk_mul_f32 v[28:29], v[28:29], v[24:25]
	v_pk_mul_f32 v[30:31], v[30:31], v[26:27]
	v_pk_mul_f32 v[20:21], v[20:21], v[16:17]
	v_pk_mul_f32 v[22:23], v[22:23], v[18:19]
	v_cvt_pk_bf16_f32 v192, v28, v29
	v_cvt_pk_bf16_f32 v193, v30, v31
	v_cvt_pk_bf16_f32 v194, v20, v21
	v_cvt_pk_bf16_f32 v195, v22, v23
	global_store_dwordx4 v[182:183], v[192:195], off nt
	s_waitcnt vmcnt(7)
	v_add_f32_e32 v140, v202, v203
	v_add_f32_e32 v141, v204, v205
	v_add_f32_e32 v140, v140, v141
	v_fmamk_f32 v140, v140, 0x3a800000, v207
	v_rsq_f32_e32 v184, v140
	s_nop 0
	v_pk_mul_f32 v[12:13], v[12:13], v[184:185] op_sel_hi:[1,0]
	v_pk_mul_f32 v[14:15], v[14:15], v[184:185] op_sel_hi:[1,0]
	v_pk_mul_f32 v[4:5], v[4:5], v[184:185] op_sel_hi:[1,0]
	v_pk_mul_f32 v[6:7], v[6:7], v[184:185] op_sel_hi:[1,0]
	v_pk_mul_f32 v[8:9], v[8:9], v[184:185] op_sel_hi:[1,0]
	v_pk_mul_f32 v[10:11], v[10:11], v[184:185] op_sel_hi:[1,0]
	v_pk_mul_f32 v[0:1], v[0:1], v[184:185] op_sel_hi:[1,0]
	v_pk_mul_f32 v[2:3], v[2:3], v[184:185] op_sel_hi:[1,0]
	v_pk_mul_f32 v[132:133], v[12:13], s[2:3]
	v_pk_mul_f32 v[134:135], v[14:15], s[2:3]
	v_pk_mul_f32 v[136:137], v[4:5], s[2:3]
	v_pk_mul_f32 v[138:139], v[6:7], s[2:3]
	v_exp_f32_e32 v132, v132
	v_exp_f32_e32 v133, v133
	v_exp_f32_e32 v134, v134
	v_exp_f32_e32 v135, v135
	v_exp_f32_e32 v136, v136
	v_exp_f32_e32 v137, v137
	v_exp_f32_e32 v138, v138
	v_exp_f32_e32 v139, v139
	v_pk_add_f32 v[132:133], v[132:133], s[100:101]
	v_pk_add_f32 v[134:135], v[134:135], s[100:101]
	v_pk_add_f32 v[136:137], v[136:137], s[100:101]
	v_pk_add_f32 v[138:139], v[138:139], s[100:101]
	v_rcp_f32_e32 v132, v132
	v_rcp_f32_e32 v133, v133
	v_rcp_f32_e32 v134, v134
	v_rcp_f32_e32 v135, v135
	v_rcp_f32_e32 v136, v136
	v_rcp_f32_e32 v137, v137
	v_rcp_f32_e32 v138, v138
	v_rcp_f32_e32 v139, v139
	v_pk_mul_f32 v[12:13], v[12:13], v[132:133]
	v_pk_mul_f32 v[14:15], v[14:15], v[134:135]
	v_pk_mul_f32 v[4:5], v[4:5], v[136:137]
	v_pk_mul_f32 v[6:7], v[6:7], v[138:139]
	v_pk_mul_f32 v[12:13], v[12:13], v[8:9]
	v_pk_mul_f32 v[14:15], v[14:15], v[10:11]
	v_pk_mul_f32 v[4:5], v[4:5], v[0:1]
	v_pk_mul_f32 v[6:7], v[6:7], v[2:3]
	v_cvt_pk_bf16_f32 v186, v12, v13
	v_cvt_pk_bf16_f32 v187, v14, v15
	v_cvt_pk_bf16_f32 v188, v4, v5
	v_cvt_pk_bf16_f32 v189, v6, v7
	global_store_dwordx4 v[182:183], v[186:189], off offset:2048 nt
	s_mov_b64 s[0:1], -1
	s_andn2_b64 vcc, exec, s[4:5]
	s_cbranch_vccnz .LBB0_1127
	s_andn2_b64 vcc, exec, s[6:7]
	s_cbranch_vccnz .LBB0_1126
	s_barrier
	s_branch .LBB0_1126
